# attention: next iteration's load bases and the loop test computed in front of the tile barrier (the wave parks there anyway) instead of after its release
# speedup vs baseline: 1.0131x; 1.0030x over previous
.Lat_qb:
	s_lshl_b32 s9, s2, 2
	s_lshr_b32 s10, s3, 1
	s_add_u32 s10, s10, s9
	s_add_u32 s11, s9, 3
	s_add_u32 s9, s9, 4
	s_lshl_b32 s18, s2, 8
	s_lshl_b32 s19, s3, 5
	s_add_u32 s18, s18, s19
	v_and_b32_e32 v235, 31, v186
	v_bfe_u32 v237, v186, 5, 1
	v_add_u32_e32 v235, s18, v235
	v_lshlrev_b32_e32 v219, 10, v235
	v_mul_u32_u24_e32 v236, 0x2cb0, v235
	v_lshl_add_u32 v220, v237, 4, v236
	v_lshl_add_u32 v197, v237, 3, v236
	global_load_dwordx4 v[102:105], v220, s[4:5] offset:0
	global_load_dwordx4 v[106:109], v220, s[4:5] offset:32
	global_load_dwordx4 v[110:113], v220, s[4:5] offset:64
	global_load_dwordx4 v[114:117], v220, s[4:5] offset:96
	s_mov_b64 s[12:13], s[4:5]
	s_add_i32 m0, s58, 0x0
	s_nop 0
	global_load_lds_dwordx4 v221, s[12:13]
	s_add_i32 m0, s58, 0x8000
	s_nop 0
	global_load_lds_dwordx4 v222, s[12:13]
	s_add_u32 s12, s12, 0xb2c00
	s_addc_u32 s13, s13, 0
	s_add_i32 m0, s58, 0x2000
	s_nop 0
	global_load_lds_dwordx4 v221, s[12:13]
	s_add_u32 s12, s12, 0xb2c00
	s_addc_u32 s13, s13, 0
	s_add_i32 m0, s58, 0x4000
	s_nop 0
	global_load_lds_dwordx4 v221, s[12:13]
	s_add_u32 s12, s12, 0xb2c00
	s_addc_u32 s13, s13, 0
	global_load_dwordx4 v[198:201], v219, s[6:7]
	s_add_i32 m0, s58, 0x6000
	s_nop 0
	global_load_lds_dwordx4 v221, s[12:13]
	s_add_u32 s14, s4, 0xb2c00
	s_addc_u32 s15, s5, 0
	s_add_i32 m0, s58, 0xa000
	s_nop 0
	global_load_lds_dwordx4 v222, s[14:15]
	v_mov_b32_e32 v230, 0xff800000
	v_mov_b32_e32 v231, 0
	v_mov_b32_e32 v0, 0
	v_mov_b32_e32 v1, 0
	v_mov_b32_e32 v2, 0
	v_mov_b32_e32 v3, 0
	v_mov_b32_e32 v4, 0
	v_mov_b32_e32 v5, 0
	v_mov_b32_e32 v6, 0
	v_mov_b32_e32 v7, 0
	v_mov_b32_e32 v8, 0
	v_mov_b32_e32 v9, 0
	v_mov_b32_e32 v10, 0
	v_mov_b32_e32 v11, 0
	v_mov_b32_e32 v12, 0
	v_mov_b32_e32 v13, 0
	v_mov_b32_e32 v14, 0
	v_mov_b32_e32 v15, 0
	v_mov_b32_e32 v16, 0
	v_mov_b32_e32 v17, 0
	v_mov_b32_e32 v18, 0
	v_mov_b32_e32 v19, 0
	v_mov_b32_e32 v20, 0
	v_mov_b32_e32 v21, 0
	v_mov_b32_e32 v22, 0
	v_mov_b32_e32 v23, 0
	v_mov_b32_e32 v24, 0
	v_mov_b32_e32 v25, 0
	v_mov_b32_e32 v26, 0
	v_mov_b32_e32 v27, 0
	v_mov_b32_e32 v28, 0
	v_mov_b32_e32 v29, 0
	v_mov_b32_e32 v30, 0
	v_mov_b32_e32 v31, 0
	s_waitcnt vmcnt(2)
	s_barrier
	ds_read_b128 v[118:121], v223 offset:0
	ds_read_b128 v[122:125], v223 offset:4096
	ds_read_b128 v[126:129], v224 offset:0
	ds_read_b128 v[130:133], v224 offset:4096
	ds_read_b128 v[134:137], v225 offset:0
	ds_read_b128 v[138:141], v225 offset:4096
	ds_read_b128 v[142:145], v226 offset:0
	ds_read_b128 v[146:149], v226 offset:4096
	s_waitcnt lgkmcnt(0)
	s_barrier
	v_mfma_f32_32x32x16_bf16 v[34:49], v[118:121], v[102:105], 0
	v_mfma_f32_32x32x16_bf16 v[50:65], v[122:125], v[102:105], 0
	v_mfma_f32_32x32x16_bf16 v[34:49], v[126:129], v[106:109], v[34:49]
	v_mfma_f32_32x32x16_bf16 v[50:65], v[130:133], v[106:109], v[50:65]
	v_mfma_f32_32x32x16_bf16 v[34:49], v[134:137], v[110:113], v[34:49]
	v_mfma_f32_32x32x16_bf16 v[50:65], v[138:141], v[110:113], v[50:65]
	v_mfma_f32_32x32x16_bf16 v[34:49], v[142:145], v[114:117], v[34:49]
	v_mfma_f32_32x32x16_bf16 v[50:65], v[146:149], v[114:117], v[50:65]
	ds_read_b128 v[118:121], v223 offset:8192
	ds_read_b128 v[122:125], v223 offset:12288
	ds_read_b128 v[126:129], v224 offset:8192
	ds_read_b128 v[130:133], v224 offset:12288
	ds_read_b128 v[134:137], v225 offset:8192
	ds_read_b128 v[138:141], v225 offset:12288
	ds_read_b128 v[142:145], v226 offset:8192
	ds_read_b128 v[146:149], v226 offset:12288
	s_waitcnt lgkmcnt(14)
	s_mov_b32 s8, 0
	s_add_u32 s18, s8, 4
	s_min_u32 s18, s18, s11
	s_mul_i32 s18, s18, 0xb2c00
	s_add_u32 s12, s4, s18
	s_addc_u32 s13, s5, 0
	s_add_u32 s19, s8, 2
	s_min_u32 s19, s19, s11
	s_mul_i32 s18, s19, 0xb2c00
	s_add_u32 s14, s4, s18
	s_addc_u32 s15, s5, 0
	s_lshl_b32 s19, s19, 3
	s_add_u32 s16, s6, s19
	s_addc_u32 s17, s7, 0
	s_nop 7
	v_lshrrev_b32_e32 v249, v229, v198
	v_lshrrev_b32_e32 v250, v229, v199
	v_bfe_i32 v235, v249, 0, 1
	v_bfe_i32 v236, v250, 0, 1
	v_bfe_i32 v237, v249, 1, 1
	v_bfe_i32 v238, v250, 1, 1
	v_bfe_i32 v239, v249, 2, 1
	v_bfe_i32 v240, v250, 2, 1
	v_bfe_i32 v241, v249, 3, 1
	v_bfe_i32 v242, v250, 3, 1
	v_bitop3_b32 v34, v34, s33, v235 bitop3:0xe4
	v_bitop3_b32 v50, v50, s33, v236 bitop3:0xe4
	v_bitop3_b32 v35, v35, s33, v237 bitop3:0xe4
	v_bitop3_b32 v51, v51, s33, v238 bitop3:0xe4
	v_bitop3_b32 v36, v36, s33, v239 bitop3:0xe4
	v_bitop3_b32 v52, v52, s33, v240 bitop3:0xe4
	v_bitop3_b32 v37, v37, s33, v241 bitop3:0xe4
	v_bitop3_b32 v53, v53, s33, v242 bitop3:0xe4
	v_max3_f32 v247, v34, s33, v50
	v_max3_f32 v248, v35, s33, v51
	v_max3_f32 v247, v247, v36, v52
	v_max3_f32 v248, v248, v37, v53
	v_bfe_i32 v235, v249, 8, 1
	v_bfe_i32 v236, v250, 8, 1
	v_bfe_i32 v237, v249, 9, 1
	v_bfe_i32 v238, v250, 9, 1
	v_bfe_i32 v239, v249, 10, 1
	v_bfe_i32 v240, v250, 10, 1
	v_bfe_i32 v241, v249, 11, 1
	v_bfe_i32 v242, v250, 11, 1
	v_bitop3_b32 v38, v38, s33, v235 bitop3:0xe4
	v_bitop3_b32 v54, v54, s33, v236 bitop3:0xe4
	v_bitop3_b32 v39, v39, s33, v237 bitop3:0xe4
	v_bitop3_b32 v55, v55, s33, v238 bitop3:0xe4
	v_bitop3_b32 v40, v40, s33, v239 bitop3:0xe4
	v_bitop3_b32 v56, v56, s33, v240 bitop3:0xe4
	v_bitop3_b32 v41, v41, s33, v241 bitop3:0xe4
	v_bitop3_b32 v57, v57, s33, v242 bitop3:0xe4
	v_max3_f32 v247, v247, v38, v54
	v_max3_f32 v248, v248, v39, v55
	v_max3_f32 v247, v247, v40, v56
	v_max3_f32 v248, v248, v41, v57
	v_bfe_i32 v235, v249, 16, 1
	v_bfe_i32 v236, v250, 16, 1
	v_bfe_i32 v237, v249, 17, 1
	v_bfe_i32 v238, v250, 17, 1
	v_bfe_i32 v239, v249, 18, 1
	v_bfe_i32 v240, v250, 18, 1
	v_bfe_i32 v241, v249, 19, 1
	v_bfe_i32 v242, v250, 19, 1
	v_bitop3_b32 v42, v42, s33, v235 bitop3:0xe4
	v_bitop3_b32 v58, v58, s33, v236 bitop3:0xe4
	v_bitop3_b32 v43, v43, s33, v237 bitop3:0xe4
	v_bitop3_b32 v59, v59, s33, v238 bitop3:0xe4
	v_bitop3_b32 v44, v44, s33, v239 bitop3:0xe4
	v_bitop3_b32 v60, v60, s33, v240 bitop3:0xe4
	v_bitop3_b32 v45, v45, s33, v241 bitop3:0xe4
	v_bitop3_b32 v61, v61, s33, v242 bitop3:0xe4
	v_max3_f32 v247, v247, v42, v58
	v_max3_f32 v248, v248, v43, v59
	v_max3_f32 v247, v247, v44, v60
	v_max3_f32 v248, v248, v45, v61
	v_bfe_i32 v235, v249, 24, 1
	v_bfe_i32 v236, v250, 24, 1
	v_bfe_i32 v237, v249, 25, 1
	v_bfe_i32 v238, v250, 25, 1
	v_bfe_i32 v239, v249, 26, 1
	v_bfe_i32 v240, v250, 26, 1
	v_bfe_i32 v241, v249, 27, 1
	v_bfe_i32 v242, v250, 27, 1
	v_bitop3_b32 v46, v46, s33, v235 bitop3:0xe4
	v_bitop3_b32 v62, v62, s33, v236 bitop3:0xe4
	v_bitop3_b32 v47, v47, s33, v237 bitop3:0xe4
	v_bitop3_b32 v63, v63, s33, v238 bitop3:0xe4
	v_bitop3_b32 v48, v48, s33, v239 bitop3:0xe4
	v_bitop3_b32 v64, v64, s33, v240 bitop3:0xe4
	v_bitop3_b32 v49, v49, s33, v241 bitop3:0xe4
	v_bitop3_b32 v65, v65, s33, v242 bitop3:0xe4
	v_max3_f32 v247, v247, v46, v62
	v_max3_f32 v248, v248, v47, v63
	v_max3_f32 v247, v247, v48, v64
	v_max3_f32 v248, v248, v49, v65
	v_max_f32_e32 v247, v247, v248
	v_mov_b32_e32 v248, v247
	s_nop 1
	v_permlane32_swap_b32_e32 v247, v248
	v_max3_f32 v247, v230, v247, v248
	v_cmp_neq_f32_e32 vcc, s33, v247
	s_nop 1
	v_cndmask_b32_e32 v248, 0, v247, vcc
	v_sub_f32_e32 v33, v230, v248
	v_mul_f32_e32 v33, 0x3e38aa3b, v33
	v_exp_f32_e32 v232, v33
	v_mul_f32_e32 v234, 0xbe38aa3b, v248
	v_mov_b32_e32 v230, v247
.Lat_loop_0:
	global_load_dwordx4 v[202:205], v219, s[16:17]
	s_add_i32 m0, s58, 0x0
	s_nop 0
	global_load_lds_dwordx4 v221, s[12:13]
	s_add_i32 m0, s58, 0xc000
	s_nop 0
	global_load_lds_dwordx4 v222, s[14:15]
	s_cmp_lt_u32 s8, s10
	s_cbranch_scc1 .Lat_full_0
	s_cmp_eq_u32 s8, s10
	s_cbranch_scc1 .Lat_last_0
.Lat_idle_0:
	s_add_u32 s8, s8, 1
	s_add_u32 s18, s8, 4
	s_min_u32 s18, s18, s11
	s_mul_i32 s18, s18, 0xb2c00
	s_add_u32 s12, s4, s18
	s_addc_u32 s13, s5, 0
	s_add_u32 s19, s8, 2
	s_min_u32 s19, s19, s11
	s_mul_i32 s18, s19, 0xb2c00
	s_add_u32 s14, s4, s18
	s_addc_u32 s15, s5, 0
	s_cmp_lt_u32 s8, s9
	s_waitcnt vmcnt(3)
	s_barrier
	s_cbranch_scc1 .Lat_loop_1
	s_branch .Lat_epilogue

.Lat_nors_f0:
	v_fmamk_f32 v34, v34, 0x3e38aa3b, v234
	v_fmamk_f32 v35, v35, 0x3e38aa3b, v234
	s_waitcnt lgkmcnt(7)
	v_mfma_f32_32x32x16_bf16 v[70:85], v[118:121], v[102:105], 0
	ds_read_b64_tr_b16 v[154:155], v227 offset:0
	ds_read_b64_tr_b16 v[156:157], v227 offset:1024
	v_fmamk_f32 v36, v36, 0x3e38aa3b, v234
	v_fmamk_f32 v37, v37, 0x3e38aa3b, v234
	v_fmamk_f32 v38, v38, 0x3e38aa3b, v234
	v_fmamk_f32 v39, v39, 0x3e38aa3b, v234
	v_fmamk_f32 v40, v40, 0x3e38aa3b, v234
	v_fmamk_f32 v41, v41, 0x3e38aa3b, v234
	v_exp_f32_e32 v34, v34
	v_exp_f32_e32 v35, v35
	v_exp_f32_e32 v36, v36
	v_exp_f32_e32 v37, v37
	v_exp_f32_e32 v38, v38
	v_exp_f32_e32 v39, v39
	s_waitcnt lgkmcnt(8)
	v_mfma_f32_32x32x16_bf16 v[86:101], v[122:125], v[102:105], 0
	ds_read_b64_tr_b16 v[158:159], v228 offset:0
	ds_read_b64_tr_b16 v[160:161], v228 offset:1024
	v_exp_f32_e32 v40, v40
	v_exp_f32_e32 v41, v41
	v_add_f32_e32 v243, v34, v38
	v_add_f32_e32 v244, v35, v39
	v_add_f32_e32 v245, v36, v40
	v_add_f32_e32 v246, v37, v41
	v_cvt_pk_bf16_f32 v34, v34, v35
	v_cvt_pk_bf16_f32 v35, v36, v37
	v_cvt_pk_bf16_f32 v36, v38, v39
	v_cvt_pk_bf16_f32 v37, v40, v41
	v_fmamk_f32 v42, v42, 0x3e38aa3b, v234
	v_fmamk_f32 v43, v43, 0x3e38aa3b, v234
	s_waitcnt lgkmcnt(9)
	v_mfma_f32_32x32x16_bf16 v[70:85], v[126:129], v[106:109], v[70:85]
	ds_read_b64_tr_b16 v[162:163], v227 offset:2048
	ds_read_b64_tr_b16 v[164:165], v227 offset:3072
	v_fmamk_f32 v44, v44, 0x3e38aa3b, v234
	v_fmamk_f32 v45, v45, 0x3e38aa3b, v234
	v_fmamk_f32 v46, v46, 0x3e38aa3b, v234
	v_fmamk_f32 v47, v47, 0x3e38aa3b, v234
	v_fmamk_f32 v48, v48, 0x3e38aa3b, v234
	v_fmamk_f32 v49, v49, 0x3e38aa3b, v234
	v_exp_f32_e32 v42, v42
	v_exp_f32_e32 v43, v43
	v_exp_f32_e32 v44, v44
	v_exp_f32_e32 v45, v45
	v_exp_f32_e32 v46, v46
	v_exp_f32_e32 v47, v47
	s_waitcnt lgkmcnt(10)
	v_mfma_f32_32x32x16_bf16 v[86:101], v[130:133], v[106:109], v[86:101]
	ds_read_b64_tr_b16 v[166:167], v228 offset:2048
	ds_read_b64_tr_b16 v[168:169], v228 offset:3072
	v_exp_f32_e32 v48, v48
	v_exp_f32_e32 v49, v49
	v_add_f32_e32 v243, v243, v42
	v_add_f32_e32 v244, v244, v43
	v_add_f32_e32 v245, v245, v44
	v_add_f32_e32 v246, v246, v45
	v_add_f32_e32 v243, v243, v46
	v_add_f32_e32 v244, v244, v47
	v_add_f32_e32 v245, v245, v48
	v_add_f32_e32 v246, v246, v49
	v_cvt_pk_bf16_f32 v42, v42, v43
	v_cvt_pk_bf16_f32 v43, v44, v45
	s_waitcnt lgkmcnt(11)
	v_mfma_f32_32x32x16_bf16 v[70:85], v[134:137], v[110:113], v[70:85]
	ds_read_b64_tr_b16 v[170:171], v227 offset:4096
	ds_read_b64_tr_b16 v[172:173], v227 offset:5120
	v_cvt_pk_bf16_f32 v44, v46, v47
	v_cvt_pk_bf16_f32 v45, v48, v49
	v_fmamk_f32 v50, v50, 0x3e38aa3b, v234
	v_fmamk_f32 v51, v51, 0x3e38aa3b, v234
	v_fmamk_f32 v52, v52, 0x3e38aa3b, v234
	v_fmamk_f32 v53, v53, 0x3e38aa3b, v234
	v_fmamk_f32 v54, v54, 0x3e38aa3b, v234
	v_fmamk_f32 v55, v55, 0x3e38aa3b, v234
	v_fmamk_f32 v56, v56, 0x3e38aa3b, v234
	v_fmamk_f32 v57, v57, 0x3e38aa3b, v234
	v_exp_f32_e32 v50, v50
	v_exp_f32_e32 v51, v51
	s_waitcnt lgkmcnt(12)
	v_mfma_f32_32x32x16_bf16 v[86:101], v[138:141], v[110:113], v[86:101]
	ds_read_b64_tr_b16 v[174:175], v228 offset:4096
	ds_read_b64_tr_b16 v[176:177], v228 offset:5120
	v_exp_f32_e32 v52, v52
	v_exp_f32_e32 v53, v53
	v_exp_f32_e32 v54, v54
	v_exp_f32_e32 v55, v55
	v_exp_f32_e32 v56, v56
	v_exp_f32_e32 v57, v57
	v_add_f32_e32 v243, v243, v50
	v_add_f32_e32 v244, v244, v51
	v_add_f32_e32 v245, v245, v52
	v_add_f32_e32 v246, v246, v53
	v_add_f32_e32 v243, v243, v54
	v_add_f32_e32 v244, v244, v55
	s_waitcnt lgkmcnt(13)
	v_mfma_f32_32x32x16_bf16 v[70:85], v[142:145], v[114:117], v[70:85]
	ds_read_b64_tr_b16 v[178:179], v227 offset:6144
	ds_read_b64_tr_b16 v[180:181], v227 offset:7168
	v_add_f32_e32 v245, v245, v56
	v_add_f32_e32 v246, v246, v57
	v_cvt_pk_bf16_f32 v50, v50, v51
	v_cvt_pk_bf16_f32 v51, v52, v53
	v_cvt_pk_bf16_f32 v52, v54, v55
	v_cvt_pk_bf16_f32 v53, v56, v57
	v_fmamk_f32 v58, v58, 0x3e38aa3b, v234
	v_fmamk_f32 v59, v59, 0x3e38aa3b, v234
	v_fmamk_f32 v60, v60, 0x3e38aa3b, v234
	v_fmamk_f32 v61, v61, 0x3e38aa3b, v234
	v_fmamk_f32 v62, v62, 0x3e38aa3b, v234
	v_fmamk_f32 v63, v63, 0x3e38aa3b, v234
	s_waitcnt lgkmcnt(14)
	v_mfma_f32_32x32x16_bf16 v[86:101], v[146:149], v[114:117], v[86:101]
	ds_read_b64_tr_b16 v[182:183], v228 offset:6144
	ds_read_b64_tr_b16 v[184:185], v228 offset:7168
	s_waitcnt lgkmcnt(14)
	v_fmamk_f32 v64, v64, 0x3e38aa3b, v234
	v_fmamk_f32 v65, v65, 0x3e38aa3b, v234
	v_exp_f32_e32 v58, v58
	v_exp_f32_e32 v59, v59
	v_exp_f32_e32 v60, v60
	v_exp_f32_e32 v61, v61
	v_exp_f32_e32 v62, v62
	v_exp_f32_e32 v63, v63
	v_exp_f32_e32 v64, v64
	v_exp_f32_e32 v65, v65
	v_add_f32_e32 v243, v243, v58
	v_add_f32_e32 v244, v244, v59
	v_add_f32_e32 v245, v245, v60
	v_add_f32_e32 v246, v246, v61
	s_waitcnt lgkmcnt(14)
	v_mfma_f32_32x32x16_bf16 v[0:15], v[154:157], v[34:37], v[0:15]
	ds_read_b128 v[118:121], v223 offset:16384
	v_add_f32_e32 v243, v243, v62
	v_add_f32_e32 v244, v244, v63
	v_add_f32_e32 v245, v245, v64
	v_add_f32_e32 v246, v246, v65
	v_cvt_pk_bf16_f32 v58, v58, v59
	v_cvt_pk_bf16_f32 v59, v60, v61
	v_cvt_pk_bf16_f32 v60, v62, v63
	v_cvt_pk_bf16_f32 v61, v64, v65
	v_add_f32_e32 v243, v243, v244
	v_add_f32_e32 v245, v245, v246
	v_add_f32_e32 v243, v243, v245
	v_fma_f32 v231, v231, v232, v243
	s_waitcnt lgkmcnt(13)
	v_mfma_f32_32x32x16_bf16 v[16:31], v[158:161], v[34:37], v[16:31]
	ds_read_b128 v[122:125], v223 offset:20480
	v_lshrrev_b32_e32 v249, v229, v200
	v_lshrrev_b32_e32 v250, v229, v201
	v_bfe_i32 v235, v249, 0, 1
	v_bfe_i32 v236, v250, 0, 1
	v_bfe_i32 v237, v249, 1, 1
	v_bfe_i32 v238, v250, 1, 1
	v_bfe_i32 v239, v249, 2, 1
	v_bfe_i32 v240, v250, 2, 1
	v_bfe_i32 v241, v249, 3, 1
	v_bfe_i32 v242, v250, 3, 1
	v_bitop3_b32 v70, v70, s33, v235 bitop3:0xe4
	s_waitcnt lgkmcnt(12)
	v_mfma_f32_32x32x16_bf16 v[0:15], v[162:165], v[42:45], v[0:15]
	ds_read_b128 v[126:129], v224 offset:16384
	v_bitop3_b32 v86, v86, s33, v236 bitop3:0xe4
	v_bitop3_b32 v71, v71, s33, v237 bitop3:0xe4
	v_bitop3_b32 v87, v87, s33, v238 bitop3:0xe4
	v_bitop3_b32 v72, v72, s33, v239 bitop3:0xe4
	v_bitop3_b32 v88, v88, s33, v240 bitop3:0xe4
	v_bitop3_b32 v73, v73, s33, v241 bitop3:0xe4
	v_bitop3_b32 v89, v89, s33, v242 bitop3:0xe4
	v_max3_f32 v247, v70, s33, v86
	v_max3_f32 v248, v71, s33, v87
	v_max3_f32 v247, v247, v72, v88
	v_max3_f32 v248, v248, v73, v89
	v_bfe_i32 v235, v249, 8, 1
	s_waitcnt lgkmcnt(11)
	v_mfma_f32_32x32x16_bf16 v[16:31], v[166:169], v[42:45], v[16:31]
	ds_read_b128 v[130:133], v224 offset:20480
	v_bfe_i32 v236, v250, 8, 1
	v_bfe_i32 v237, v249, 9, 1
	v_bfe_i32 v238, v250, 9, 1
	v_bfe_i32 v239, v249, 10, 1
	v_bfe_i32 v240, v250, 10, 1
	v_bfe_i32 v241, v249, 11, 1
	v_bfe_i32 v242, v250, 11, 1
	v_bitop3_b32 v74, v74, s33, v235 bitop3:0xe4
	v_bitop3_b32 v90, v90, s33, v236 bitop3:0xe4
	v_bitop3_b32 v75, v75, s33, v237 bitop3:0xe4
	v_bitop3_b32 v91, v91, s33, v238 bitop3:0xe4
	v_bitop3_b32 v76, v76, s33, v239 bitop3:0xe4
	s_waitcnt lgkmcnt(10)
	v_mfma_f32_32x32x16_bf16 v[0:15], v[170:173], v[50:53], v[0:15]
	ds_read_b128 v[134:137], v225 offset:16384
	v_bitop3_b32 v92, v92, s33, v240 bitop3:0xe4
	v_bitop3_b32 v77, v77, s33, v241 bitop3:0xe4
	v_bitop3_b32 v93, v93, s33, v242 bitop3:0xe4
	v_max3_f32 v247, v247, v74, v90
	v_max3_f32 v248, v248, v75, v91
	v_max3_f32 v247, v247, v76, v92
	v_max3_f32 v248, v248, v77, v93
	v_bfe_i32 v235, v249, 16, 1
	v_bfe_i32 v236, v250, 16, 1
	v_bfe_i32 v237, v249, 17, 1
	v_bfe_i32 v238, v250, 17, 1
	v_bfe_i32 v239, v249, 18, 1
	s_waitcnt lgkmcnt(9)
	v_mfma_f32_32x32x16_bf16 v[16:31], v[174:177], v[50:53], v[16:31]
	ds_read_b128 v[138:141], v225 offset:20480
	v_bfe_i32 v240, v250, 18, 1
	v_bfe_i32 v241, v249, 19, 1
	v_bfe_i32 v242, v250, 19, 1
	v_bitop3_b32 v78, v78, s33, v235 bitop3:0xe4
	v_bitop3_b32 v94, v94, s33, v236 bitop3:0xe4
	v_bitop3_b32 v79, v79, s33, v237 bitop3:0xe4
	v_bitop3_b32 v95, v95, s33, v238 bitop3:0xe4
	v_bitop3_b32 v80, v80, s33, v239 bitop3:0xe4
	v_bitop3_b32 v96, v96, s33, v240 bitop3:0xe4
	v_bitop3_b32 v81, v81, s33, v241 bitop3:0xe4
	v_bitop3_b32 v97, v97, s33, v242 bitop3:0xe4
	v_max3_f32 v247, v247, v78, v94
	s_waitcnt lgkmcnt(8)
	v_mfma_f32_32x32x16_bf16 v[0:15], v[178:181], v[58:61], v[0:15]
	ds_read_b128 v[142:145], v226 offset:16384
	v_max3_f32 v248, v248, v79, v95
	v_max3_f32 v247, v247, v80, v96
	v_max3_f32 v248, v248, v81, v97
	v_bfe_i32 v235, v249, 24, 1
	v_bfe_i32 v236, v250, 24, 1
	v_bfe_i32 v237, v249, 25, 1
	v_bfe_i32 v238, v250, 25, 1
	v_bfe_i32 v239, v249, 26, 1
	v_bfe_i32 v240, v250, 26, 1
	v_bfe_i32 v241, v249, 27, 1
	v_bfe_i32 v242, v250, 27, 1
	v_bitop3_b32 v82, v82, s33, v235 bitop3:0xe4
	s_waitcnt lgkmcnt(7)
	v_mfma_f32_32x32x16_bf16 v[16:31], v[182:185], v[58:61], v[16:31]
	ds_read_b128 v[146:149], v226 offset:20480
	v_bitop3_b32 v98, v98, s33, v236 bitop3:0xe4
	v_bitop3_b32 v83, v83, s33, v237 bitop3:0xe4
	v_bitop3_b32 v99, v99, s33, v238 bitop3:0xe4
	v_bitop3_b32 v84, v84, s33, v239 bitop3:0xe4
	v_bitop3_b32 v100, v100, s33, v240 bitop3:0xe4
	v_bitop3_b32 v85, v85, s33, v241 bitop3:0xe4
	v_bitop3_b32 v101, v101, s33, v242 bitop3:0xe4
	v_max3_f32 v247, v247, v82, v98
	v_max3_f32 v248, v248, v83, v99
	v_max3_f32 v247, v247, v84, v100
	v_max3_f32 v248, v248, v85, v101
	v_max_f32_e32 v247, v247, v248
	v_mov_b32_e32 v248, v247
	s_nop 1
	v_permlane32_swap_b32_e32 v247, v248
	v_max3_f32 v247, v230, v247, v248
	v_cmp_neq_f32_e32 vcc, s33, v247
	s_nop 1
	v_cndmask_b32_e32 v248, 0, v247, vcc
	v_sub_f32_e32 v33, v230, v248
	v_mul_f32_e32 v33, 0x3e38aa3b, v33
	v_exp_f32_e32 v232, v33
	v_mul_f32_e32 v234, 0xbe38aa3b, v248
	v_mov_b32_e32 v230, v247
	s_add_u32 s8, s8, 1
	s_add_u32 s18, s8, 4
	s_min_u32 s18, s18, s11
	s_mul_i32 s18, s18, 0xb2c00
	s_add_u32 s12, s4, s18
	s_addc_u32 s13, s5, 0
	s_add_u32 s19, s8, 2
	s_min_u32 s19, s19, s11
	s_mul_i32 s18, s19, 0xb2c00
	s_add_u32 s14, s4, s18
	s_addc_u32 s15, s5, 0
	s_cmp_lt_u32 s8, s9
	s_waitcnt vmcnt(3)
	s_barrier
	s_cbranch_scc1 .Lat_loop_1
	s_branch .Lat_epilogue

.Lat_nors_l0:
	v_fmamk_f32 v34, v34, 0x3e38aa3b, v234
	v_fmamk_f32 v35, v35, 0x3e38aa3b, v234
	v_fmamk_f32 v36, v36, 0x3e38aa3b, v234
	ds_read_b64_tr_b16 v[168:169], v228 offset:3072
	s_waitcnt lgkmcnt(14)
	v_fmamk_f32 v37, v37, 0x3e38aa3b, v234
	v_fmamk_f32 v38, v38, 0x3e38aa3b, v234
	v_fmamk_f32 v39, v39, 0x3e38aa3b, v234
	ds_read_b64_tr_b16 v[170:171], v227 offset:4096
	s_waitcnt lgkmcnt(14)
	v_fmamk_f32 v40, v40, 0x3e38aa3b, v234
	v_fmamk_f32 v41, v41, 0x3e38aa3b, v234
	v_exp_f32_e32 v34, v34
	ds_read_b64_tr_b16 v[172:173], v227 offset:5120
	s_waitcnt lgkmcnt(14)
	v_exp_f32_e32 v35, v35
	v_exp_f32_e32 v36, v36
	v_exp_f32_e32 v37, v37
	ds_read_b64_tr_b16 v[174:175], v228 offset:4096
	s_waitcnt lgkmcnt(14)
	v_exp_f32_e32 v38, v38
	v_exp_f32_e32 v39, v39
	v_exp_f32_e32 v40, v40
	ds_read_b64_tr_b16 v[176:177], v228 offset:5120
	s_waitcnt lgkmcnt(14)
	v_exp_f32_e32 v41, v41
	v_add_f32_e32 v243, v34, v38
	v_add_f32_e32 v244, v35, v39
	ds_read_b64_tr_b16 v[178:179], v227 offset:6144
	s_waitcnt lgkmcnt(14)
	v_add_f32_e32 v245, v36, v40
	v_add_f32_e32 v246, v37, v41
	v_cvt_pk_bf16_f32 v34, v34, v35
	ds_read_b64_tr_b16 v[180:181], v227 offset:7168
	s_waitcnt lgkmcnt(14)
	v_cvt_pk_bf16_f32 v35, v36, v37
	v_cvt_pk_bf16_f32 v36, v38, v39
	v_cvt_pk_bf16_f32 v37, v40, v41
	ds_read_b64_tr_b16 v[182:183], v228 offset:6144
	s_waitcnt lgkmcnt(14)
	s_waitcnt lgkmcnt(13)
	v_mfma_f32_32x32x16_bf16 v[0:15], v[154:157], v[34:37], v[0:15]
	s_waitcnt lgkmcnt(11)
	v_mfma_f32_32x32x16_bf16 v[16:31], v[158:161], v[34:37], v[16:31]
	v_fmamk_f32 v42, v42, 0x3e38aa3b, v234
	v_fmamk_f32 v43, v43, 0x3e38aa3b, v234
	v_fmamk_f32 v44, v44, 0x3e38aa3b, v234
	ds_read_b64_tr_b16 v[184:185], v228 offset:7168
	v_fmamk_f32 v45, v45, 0x3e38aa3b, v234
	v_fmamk_f32 v46, v46, 0x3e38aa3b, v234
	v_fmamk_f32 v47, v47, 0x3e38aa3b, v234
	v_fmamk_f32 v48, v48, 0x3e38aa3b, v234
	v_fmamk_f32 v49, v49, 0x3e38aa3b, v234
	v_exp_f32_e32 v42, v42
	v_exp_f32_e32 v43, v43
	v_exp_f32_e32 v44, v44
	v_exp_f32_e32 v45, v45
	v_exp_f32_e32 v46, v46
	v_exp_f32_e32 v47, v47
	v_exp_f32_e32 v48, v48
	v_exp_f32_e32 v49, v49
	v_add_f32_e32 v243, v243, v42
	v_add_f32_e32 v244, v244, v43
	v_add_f32_e32 v245, v245, v44
	v_add_f32_e32 v246, v246, v45
	v_add_f32_e32 v243, v243, v46
	v_add_f32_e32 v244, v244, v47
	v_add_f32_e32 v245, v245, v48
	v_add_f32_e32 v246, v246, v49
	v_cvt_pk_bf16_f32 v42, v42, v43
	v_cvt_pk_bf16_f32 v43, v44, v45
	v_cvt_pk_bf16_f32 v44, v46, v47
	v_cvt_pk_bf16_f32 v45, v48, v49
	s_waitcnt lgkmcnt(10)
	v_mfma_f32_32x32x16_bf16 v[0:15], v[162:165], v[42:45], v[0:15]
	s_waitcnt lgkmcnt(8)
	v_mfma_f32_32x32x16_bf16 v[16:31], v[166:169], v[42:45], v[16:31]
	v_fmamk_f32 v50, v50, 0x3e38aa3b, v234
	v_fmamk_f32 v51, v51, 0x3e38aa3b, v234
	v_fmamk_f32 v52, v52, 0x3e38aa3b, v234
	v_fmamk_f32 v53, v53, 0x3e38aa3b, v234
	v_fmamk_f32 v54, v54, 0x3e38aa3b, v234
	v_fmamk_f32 v55, v55, 0x3e38aa3b, v234
	v_fmamk_f32 v56, v56, 0x3e38aa3b, v234
	v_fmamk_f32 v57, v57, 0x3e38aa3b, v234
	v_exp_f32_e32 v50, v50
	v_exp_f32_e32 v51, v51
	v_exp_f32_e32 v52, v52
	v_exp_f32_e32 v53, v53
	v_exp_f32_e32 v54, v54
	v_exp_f32_e32 v55, v55
	v_exp_f32_e32 v56, v56
	v_exp_f32_e32 v57, v57
	v_add_f32_e32 v243, v243, v50
	v_add_f32_e32 v244, v244, v51
	v_add_f32_e32 v245, v245, v52
	v_add_f32_e32 v246, v246, v53
	v_add_f32_e32 v243, v243, v54
	v_add_f32_e32 v244, v244, v55
	v_add_f32_e32 v245, v245, v56
	v_add_f32_e32 v246, v246, v57
	v_cvt_pk_bf16_f32 v50, v50, v51
	v_cvt_pk_bf16_f32 v51, v52, v53
	v_cvt_pk_bf16_f32 v52, v54, v55
	v_cvt_pk_bf16_f32 v53, v56, v57
	s_waitcnt lgkmcnt(6)
	v_mfma_f32_32x32x16_bf16 v[0:15], v[170:173], v[50:53], v[0:15]
	s_waitcnt lgkmcnt(4)
	v_mfma_f32_32x32x16_bf16 v[16:31], v[174:177], v[50:53], v[16:31]
	v_fmamk_f32 v58, v58, 0x3e38aa3b, v234
	v_fmamk_f32 v59, v59, 0x3e38aa3b, v234
	v_fmamk_f32 v60, v60, 0x3e38aa3b, v234
	v_fmamk_f32 v61, v61, 0x3e38aa3b, v234
	v_fmamk_f32 v62, v62, 0x3e38aa3b, v234
	v_fmamk_f32 v63, v63, 0x3e38aa3b, v234
	v_fmamk_f32 v64, v64, 0x3e38aa3b, v234
	v_fmamk_f32 v65, v65, 0x3e38aa3b, v234
	v_exp_f32_e32 v58, v58
	v_exp_f32_e32 v59, v59
	v_exp_f32_e32 v60, v60
	v_exp_f32_e32 v61, v61
	v_exp_f32_e32 v62, v62
	v_exp_f32_e32 v63, v63
	v_exp_f32_e32 v64, v64
	v_exp_f32_e32 v65, v65
	v_add_f32_e32 v243, v243, v58
	v_add_f32_e32 v244, v244, v59
	v_add_f32_e32 v245, v245, v60
	v_add_f32_e32 v246, v246, v61
	v_add_f32_e32 v243, v243, v62
	v_add_f32_e32 v244, v244, v63
	v_add_f32_e32 v245, v245, v64
	v_add_f32_e32 v246, v246, v65
	v_cvt_pk_bf16_f32 v58, v58, v59
	v_cvt_pk_bf16_f32 v59, v60, v61
	v_cvt_pk_bf16_f32 v60, v62, v63
	v_cvt_pk_bf16_f32 v61, v64, v65
	v_add_f32_e32 v243, v243, v244
	v_add_f32_e32 v245, v245, v246
	v_add_f32_e32 v243, v243, v245
	v_fma_f32 v231, v231, v232, v243
	s_waitcnt lgkmcnt(2)
	v_mfma_f32_32x32x16_bf16 v[0:15], v[178:181], v[58:61], v[0:15]
	s_waitcnt lgkmcnt(0)
	v_mfma_f32_32x32x16_bf16 v[16:31], v[182:185], v[58:61], v[16:31]
	s_add_u32 s8, s8, 1
	s_add_u32 s18, s8, 4
	s_min_u32 s18, s18, s11
	s_mul_i32 s18, s18, 0xb2c00
	s_add_u32 s12, s4, s18
	s_addc_u32 s13, s5, 0
	s_add_u32 s19, s8, 2
	s_min_u32 s19, s19, s11
	s_mul_i32 s18, s19, 0xb2c00
	s_add_u32 s14, s4, s18
	s_addc_u32 s15, s5, 0
	s_cmp_lt_u32 s8, s9
	s_waitcnt vmcnt(3)
	s_barrier
	s_cbranch_scc1 .Lat_loop_1
	s_branch .Lat_epilogue
.Lat_loop_1:
	s_add_i32 m0, s58, 0x2000
	s_nop 0
	global_load_lds_dwordx4 v221, s[12:13]
	s_add_i32 m0, s58, 0xe000
	s_nop 0
	global_load_lds_dwordx4 v222, s[14:15]
	s_cmp_lt_u32 s8, s10
	s_cbranch_scc1 .Lat_full_1
	s_cmp_eq_u32 s8, s10
	s_cbranch_scc1 .Lat_last_1
.Lat_idle_1:
	s_add_u32 s8, s8, 1
	s_add_u32 s18, s8, 4
	s_min_u32 s18, s18, s11
	s_mul_i32 s18, s18, 0xb2c00
	s_add_u32 s12, s4, s18
	s_addc_u32 s13, s5, 0
	s_add_u32 s19, s8, 2
	s_min_u32 s19, s19, s11
	s_mul_i32 s18, s19, 0xb2c00
	s_add_u32 s14, s4, s18
	s_addc_u32 s15, s5, 0
	s_lshl_b32 s19, s19, 3
	s_add_u32 s16, s6, s19
	s_addc_u32 s17, s7, 0
	s_cmp_lt_u32 s8, s9
	s_waitcnt vmcnt(2)
	s_barrier
	s_cbranch_scc1 .Lat_loop_2
	s_branch .Lat_epilogue

.Lat_nors_f1:
	v_fmamk_f32 v70, v70, 0x3e38aa3b, v234
	v_fmamk_f32 v71, v71, 0x3e38aa3b, v234
	s_waitcnt lgkmcnt(7)
	v_mfma_f32_32x32x16_bf16 v[34:49], v[118:121], v[102:105], 0
	ds_read_b64_tr_b16 v[154:155], v227 offset:8192
	ds_read_b64_tr_b16 v[156:157], v227 offset:9216
	v_fmamk_f32 v72, v72, 0x3e38aa3b, v234
	v_fmamk_f32 v73, v73, 0x3e38aa3b, v234
	v_fmamk_f32 v74, v74, 0x3e38aa3b, v234
	v_fmamk_f32 v75, v75, 0x3e38aa3b, v234
	v_fmamk_f32 v76, v76, 0x3e38aa3b, v234
	v_fmamk_f32 v77, v77, 0x3e38aa3b, v234
	v_exp_f32_e32 v70, v70
	v_exp_f32_e32 v71, v71
	v_exp_f32_e32 v72, v72
	v_exp_f32_e32 v73, v73
	v_exp_f32_e32 v74, v74
	v_exp_f32_e32 v75, v75
	s_waitcnt lgkmcnt(8)
	v_mfma_f32_32x32x16_bf16 v[50:65], v[122:125], v[102:105], 0
	ds_read_b64_tr_b16 v[158:159], v228 offset:8192
	ds_read_b64_tr_b16 v[160:161], v228 offset:9216
	v_exp_f32_e32 v76, v76
	v_exp_f32_e32 v77, v77
	v_add_f32_e32 v243, v70, v74
	v_add_f32_e32 v244, v71, v75
	v_add_f32_e32 v245, v72, v76
	v_add_f32_e32 v246, v73, v77
	v_cvt_pk_bf16_f32 v70, v70, v71
	v_cvt_pk_bf16_f32 v71, v72, v73
	v_cvt_pk_bf16_f32 v72, v74, v75
	v_cvt_pk_bf16_f32 v73, v76, v77
	v_fmamk_f32 v78, v78, 0x3e38aa3b, v234
	v_fmamk_f32 v79, v79, 0x3e38aa3b, v234
	s_waitcnt lgkmcnt(9)
	v_mfma_f32_32x32x16_bf16 v[34:49], v[126:129], v[106:109], v[34:49]
	ds_read_b64_tr_b16 v[162:163], v227 offset:10240
	ds_read_b64_tr_b16 v[164:165], v227 offset:11264
	v_fmamk_f32 v80, v80, 0x3e38aa3b, v234
	v_fmamk_f32 v81, v81, 0x3e38aa3b, v234
	v_fmamk_f32 v82, v82, 0x3e38aa3b, v234
	v_fmamk_f32 v83, v83, 0x3e38aa3b, v234
	v_fmamk_f32 v84, v84, 0x3e38aa3b, v234
	v_fmamk_f32 v85, v85, 0x3e38aa3b, v234
	v_exp_f32_e32 v78, v78
	v_exp_f32_e32 v79, v79
	v_exp_f32_e32 v80, v80
	v_exp_f32_e32 v81, v81
	v_exp_f32_e32 v82, v82
	v_exp_f32_e32 v83, v83
	s_waitcnt lgkmcnt(10)
	v_mfma_f32_32x32x16_bf16 v[50:65], v[130:133], v[106:109], v[50:65]
	ds_read_b64_tr_b16 v[166:167], v228 offset:10240
	ds_read_b64_tr_b16 v[168:169], v228 offset:11264
	v_exp_f32_e32 v84, v84
	v_exp_f32_e32 v85, v85
	v_add_f32_e32 v243, v243, v78
	v_add_f32_e32 v244, v244, v79
	v_add_f32_e32 v245, v245, v80
	v_add_f32_e32 v246, v246, v81
	v_add_f32_e32 v243, v243, v82
	v_add_f32_e32 v244, v244, v83
	v_add_f32_e32 v245, v245, v84
	v_add_f32_e32 v246, v246, v85
	v_cvt_pk_bf16_f32 v78, v78, v79
	v_cvt_pk_bf16_f32 v79, v80, v81
	s_waitcnt lgkmcnt(11)
	v_mfma_f32_32x32x16_bf16 v[34:49], v[134:137], v[110:113], v[34:49]
	ds_read_b64_tr_b16 v[170:171], v227 offset:12288
	ds_read_b64_tr_b16 v[172:173], v227 offset:13312
	v_cvt_pk_bf16_f32 v80, v82, v83
	v_cvt_pk_bf16_f32 v81, v84, v85
	v_fmamk_f32 v86, v86, 0x3e38aa3b, v234
	v_fmamk_f32 v87, v87, 0x3e38aa3b, v234
	v_fmamk_f32 v88, v88, 0x3e38aa3b, v234
	v_fmamk_f32 v89, v89, 0x3e38aa3b, v234
	v_fmamk_f32 v90, v90, 0x3e38aa3b, v234
	v_fmamk_f32 v91, v91, 0x3e38aa3b, v234
	v_fmamk_f32 v92, v92, 0x3e38aa3b, v234
	v_fmamk_f32 v93, v93, 0x3e38aa3b, v234
	v_exp_f32_e32 v86, v86
	v_exp_f32_e32 v87, v87
	s_waitcnt lgkmcnt(12)
	v_mfma_f32_32x32x16_bf16 v[50:65], v[138:141], v[110:113], v[50:65]
	ds_read_b64_tr_b16 v[174:175], v228 offset:12288
	ds_read_b64_tr_b16 v[176:177], v228 offset:13312
	v_exp_f32_e32 v88, v88
	v_exp_f32_e32 v89, v89
	v_exp_f32_e32 v90, v90
	v_exp_f32_e32 v91, v91
	v_exp_f32_e32 v92, v92
	v_exp_f32_e32 v93, v93
	v_add_f32_e32 v243, v243, v86
	v_add_f32_e32 v244, v244, v87
	v_add_f32_e32 v245, v245, v88
	v_add_f32_e32 v246, v246, v89
	v_add_f32_e32 v243, v243, v90
	v_add_f32_e32 v244, v244, v91
	s_waitcnt lgkmcnt(13)
	v_mfma_f32_32x32x16_bf16 v[34:49], v[142:145], v[114:117], v[34:49]
	ds_read_b64_tr_b16 v[178:179], v227 offset:14336
	ds_read_b64_tr_b16 v[180:181], v227 offset:15360
	v_add_f32_e32 v245, v245, v92
	v_add_f32_e32 v246, v246, v93
	v_cvt_pk_bf16_f32 v86, v86, v87
	v_cvt_pk_bf16_f32 v87, v88, v89
	v_cvt_pk_bf16_f32 v88, v90, v91
	v_cvt_pk_bf16_f32 v89, v92, v93
	v_fmamk_f32 v94, v94, 0x3e38aa3b, v234
	v_fmamk_f32 v95, v95, 0x3e38aa3b, v234
	v_fmamk_f32 v96, v96, 0x3e38aa3b, v234
	v_fmamk_f32 v97, v97, 0x3e38aa3b, v234
	v_fmamk_f32 v98, v98, 0x3e38aa3b, v234
	v_fmamk_f32 v99, v99, 0x3e38aa3b, v234
	s_waitcnt lgkmcnt(14)
	v_mfma_f32_32x32x16_bf16 v[50:65], v[146:149], v[114:117], v[50:65]
	ds_read_b64_tr_b16 v[182:183], v228 offset:14336
	ds_read_b64_tr_b16 v[184:185], v228 offset:15360
	s_waitcnt lgkmcnt(14)
	v_fmamk_f32 v100, v100, 0x3e38aa3b, v234
	v_fmamk_f32 v101, v101, 0x3e38aa3b, v234
	v_exp_f32_e32 v94, v94
	v_exp_f32_e32 v95, v95
	v_exp_f32_e32 v96, v96
	v_exp_f32_e32 v97, v97
	v_exp_f32_e32 v98, v98
	v_exp_f32_e32 v99, v99
	v_exp_f32_e32 v100, v100
	v_exp_f32_e32 v101, v101
	v_add_f32_e32 v243, v243, v94
	v_add_f32_e32 v244, v244, v95
	v_add_f32_e32 v245, v245, v96
	v_add_f32_e32 v246, v246, v97
	s_waitcnt lgkmcnt(14)
	v_mfma_f32_32x32x16_bf16 v[0:15], v[154:157], v[70:73], v[0:15]
	ds_read_b128 v[118:121], v223 offset:24576
	v_add_f32_e32 v243, v243, v98
	v_add_f32_e32 v244, v244, v99
	v_add_f32_e32 v245, v245, v100
	v_add_f32_e32 v246, v246, v101
	v_cvt_pk_bf16_f32 v94, v94, v95
	v_cvt_pk_bf16_f32 v95, v96, v97
	v_cvt_pk_bf16_f32 v96, v98, v99
	v_cvt_pk_bf16_f32 v97, v100, v101
	v_add_f32_e32 v243, v243, v244
	v_add_f32_e32 v245, v245, v246
	v_add_f32_e32 v243, v243, v245
	v_fma_f32 v231, v231, v232, v243
	s_waitcnt lgkmcnt(13)
	v_mfma_f32_32x32x16_bf16 v[16:31], v[158:161], v[70:73], v[16:31]
	ds_read_b128 v[122:125], v223 offset:28672
	s_waitcnt vmcnt(4)
	v_lshrrev_b32_e32 v249, v229, v202
	v_lshrrev_b32_e32 v250, v229, v203
	v_bfe_i32 v235, v249, 0, 1
	v_bfe_i32 v236, v250, 0, 1
	v_bfe_i32 v237, v249, 1, 1
	v_bfe_i32 v238, v250, 1, 1
	v_bfe_i32 v239, v249, 2, 1
	v_bfe_i32 v240, v250, 2, 1
	v_bfe_i32 v241, v249, 3, 1
	v_bfe_i32 v242, v250, 3, 1
	v_bitop3_b32 v34, v34, s33, v235 bitop3:0xe4
	s_waitcnt lgkmcnt(12)
	v_mfma_f32_32x32x16_bf16 v[0:15], v[162:165], v[78:81], v[0:15]
	ds_read_b128 v[126:129], v224 offset:24576
	v_bitop3_b32 v50, v50, s33, v236 bitop3:0xe4
	v_bitop3_b32 v35, v35, s33, v237 bitop3:0xe4
	v_bitop3_b32 v51, v51, s33, v238 bitop3:0xe4
	v_bitop3_b32 v36, v36, s33, v239 bitop3:0xe4
	v_bitop3_b32 v52, v52, s33, v240 bitop3:0xe4
	v_bitop3_b32 v37, v37, s33, v241 bitop3:0xe4
	v_bitop3_b32 v53, v53, s33, v242 bitop3:0xe4
	v_max3_f32 v247, v34, s33, v50
	v_max3_f32 v248, v35, s33, v51
	v_max3_f32 v247, v247, v36, v52
	v_max3_f32 v248, v248, v37, v53
	v_bfe_i32 v235, v249, 8, 1
	s_waitcnt lgkmcnt(11)
	v_mfma_f32_32x32x16_bf16 v[16:31], v[166:169], v[78:81], v[16:31]
	ds_read_b128 v[130:133], v224 offset:28672
	v_bfe_i32 v236, v250, 8, 1
	v_bfe_i32 v237, v249, 9, 1
	v_bfe_i32 v238, v250, 9, 1
	v_bfe_i32 v239, v249, 10, 1
	v_bfe_i32 v240, v250, 10, 1
	v_bfe_i32 v241, v249, 11, 1
	v_bfe_i32 v242, v250, 11, 1
	v_bitop3_b32 v38, v38, s33, v235 bitop3:0xe4
	v_bitop3_b32 v54, v54, s33, v236 bitop3:0xe4
	v_bitop3_b32 v39, v39, s33, v237 bitop3:0xe4
	v_bitop3_b32 v55, v55, s33, v238 bitop3:0xe4
	v_bitop3_b32 v40, v40, s33, v239 bitop3:0xe4
	s_waitcnt lgkmcnt(10)
	v_mfma_f32_32x32x16_bf16 v[0:15], v[170:173], v[86:89], v[0:15]
	ds_read_b128 v[134:137], v225 offset:24576
	v_bitop3_b32 v56, v56, s33, v240 bitop3:0xe4
	v_bitop3_b32 v41, v41, s33, v241 bitop3:0xe4
	v_bitop3_b32 v57, v57, s33, v242 bitop3:0xe4
	v_max3_f32 v247, v247, v38, v54
	v_max3_f32 v248, v248, v39, v55
	v_max3_f32 v247, v247, v40, v56
	v_max3_f32 v248, v248, v41, v57
	v_bfe_i32 v235, v249, 16, 1
	v_bfe_i32 v236, v250, 16, 1
	v_bfe_i32 v237, v249, 17, 1
	v_bfe_i32 v238, v250, 17, 1
	v_bfe_i32 v239, v249, 18, 1
	s_waitcnt lgkmcnt(9)
	v_mfma_f32_32x32x16_bf16 v[16:31], v[174:177], v[86:89], v[16:31]
	ds_read_b128 v[138:141], v225 offset:28672
	v_bfe_i32 v240, v250, 18, 1
	v_bfe_i32 v241, v249, 19, 1
	v_bfe_i32 v242, v250, 19, 1
	v_bitop3_b32 v42, v42, s33, v235 bitop3:0xe4
	v_bitop3_b32 v58, v58, s33, v236 bitop3:0xe4
	v_bitop3_b32 v43, v43, s33, v237 bitop3:0xe4
	v_bitop3_b32 v59, v59, s33, v238 bitop3:0xe4
	v_bitop3_b32 v44, v44, s33, v239 bitop3:0xe4
	v_bitop3_b32 v60, v60, s33, v240 bitop3:0xe4
	v_bitop3_b32 v45, v45, s33, v241 bitop3:0xe4
	v_bitop3_b32 v61, v61, s33, v242 bitop3:0xe4
	v_max3_f32 v247, v247, v42, v58
	s_waitcnt lgkmcnt(8)
	v_mfma_f32_32x32x16_bf16 v[0:15], v[178:181], v[94:97], v[0:15]
	ds_read_b128 v[142:145], v226 offset:24576
	v_max3_f32 v248, v248, v43, v59
	v_max3_f32 v247, v247, v44, v60
	v_max3_f32 v248, v248, v45, v61
	v_bfe_i32 v235, v249, 24, 1
	v_bfe_i32 v236, v250, 24, 1
	v_bfe_i32 v237, v249, 25, 1
	v_bfe_i32 v238, v250, 25, 1
	v_bfe_i32 v239, v249, 26, 1
	v_bfe_i32 v240, v250, 26, 1
	v_bfe_i32 v241, v249, 27, 1
	v_bfe_i32 v242, v250, 27, 1
	v_bitop3_b32 v46, v46, s33, v235 bitop3:0xe4
	s_waitcnt lgkmcnt(7)
	v_mfma_f32_32x32x16_bf16 v[16:31], v[182:185], v[94:97], v[16:31]
	ds_read_b128 v[146:149], v226 offset:28672
	v_bitop3_b32 v62, v62, s33, v236 bitop3:0xe4
	v_bitop3_b32 v47, v47, s33, v237 bitop3:0xe4
	v_bitop3_b32 v63, v63, s33, v238 bitop3:0xe4
	v_bitop3_b32 v48, v48, s33, v239 bitop3:0xe4
	v_bitop3_b32 v64, v64, s33, v240 bitop3:0xe4
	v_bitop3_b32 v49, v49, s33, v241 bitop3:0xe4
	v_bitop3_b32 v65, v65, s33, v242 bitop3:0xe4
	v_max3_f32 v247, v247, v46, v62
	v_max3_f32 v248, v248, v47, v63
	v_max3_f32 v247, v247, v48, v64
	v_max3_f32 v248, v248, v49, v65
	v_max_f32_e32 v247, v247, v248
	v_mov_b32_e32 v248, v247
	s_nop 1
	v_permlane32_swap_b32_e32 v247, v248
	v_max3_f32 v247, v230, v247, v248
	v_cmp_neq_f32_e32 vcc, s33, v247
	s_nop 1
	v_cndmask_b32_e32 v248, 0, v247, vcc
	v_sub_f32_e32 v33, v230, v248
	v_mul_f32_e32 v33, 0x3e38aa3b, v33
	v_exp_f32_e32 v232, v33
	v_mul_f32_e32 v234, 0xbe38aa3b, v248
	v_mov_b32_e32 v230, v247
	s_add_u32 s8, s8, 1
	s_add_u32 s18, s8, 4
	s_min_u32 s18, s18, s11
	s_mul_i32 s18, s18, 0xb2c00
	s_add_u32 s12, s4, s18
	s_addc_u32 s13, s5, 0
	s_add_u32 s19, s8, 2
	s_min_u32 s19, s19, s11
	s_mul_i32 s18, s19, 0xb2c00
	s_add_u32 s14, s4, s18
	s_addc_u32 s15, s5, 0
	s_lshl_b32 s19, s19, 3
	s_add_u32 s16, s6, s19
	s_addc_u32 s17, s7, 0
	s_cmp_lt_u32 s8, s9
	s_waitcnt vmcnt(2)
	s_barrier
	s_cbranch_scc1 .Lat_loop_2
	s_branch .Lat_epilogue

.Lat_nors_l1:
	v_fmamk_f32 v70, v70, 0x3e38aa3b, v234
	v_fmamk_f32 v71, v71, 0x3e38aa3b, v234
	v_fmamk_f32 v72, v72, 0x3e38aa3b, v234
	ds_read_b64_tr_b16 v[168:169], v228 offset:11264
	s_waitcnt lgkmcnt(14)
	v_fmamk_f32 v73, v73, 0x3e38aa3b, v234
	v_fmamk_f32 v74, v74, 0x3e38aa3b, v234
	v_fmamk_f32 v75, v75, 0x3e38aa3b, v234
	ds_read_b64_tr_b16 v[170:171], v227 offset:12288
	s_waitcnt lgkmcnt(14)
	v_fmamk_f32 v76, v76, 0x3e38aa3b, v234
	v_fmamk_f32 v77, v77, 0x3e38aa3b, v234
	v_exp_f32_e32 v70, v70
	ds_read_b64_tr_b16 v[172:173], v227 offset:13312
	s_waitcnt lgkmcnt(14)
	v_exp_f32_e32 v71, v71
	v_exp_f32_e32 v72, v72
	v_exp_f32_e32 v73, v73
	ds_read_b64_tr_b16 v[174:175], v228 offset:12288
	s_waitcnt lgkmcnt(14)
	v_exp_f32_e32 v74, v74
	v_exp_f32_e32 v75, v75
	v_exp_f32_e32 v76, v76
	ds_read_b64_tr_b16 v[176:177], v228 offset:13312
	s_waitcnt lgkmcnt(14)
	v_exp_f32_e32 v77, v77
	v_add_f32_e32 v243, v70, v74
	v_add_f32_e32 v244, v71, v75
	ds_read_b64_tr_b16 v[178:179], v227 offset:14336
	s_waitcnt lgkmcnt(14)
	v_add_f32_e32 v245, v72, v76
	v_add_f32_e32 v246, v73, v77
	v_cvt_pk_bf16_f32 v70, v70, v71
	ds_read_b64_tr_b16 v[180:181], v227 offset:15360
	s_waitcnt lgkmcnt(14)
	v_cvt_pk_bf16_f32 v71, v72, v73
	v_cvt_pk_bf16_f32 v72, v74, v75
	v_cvt_pk_bf16_f32 v73, v76, v77
	ds_read_b64_tr_b16 v[182:183], v228 offset:14336
	s_waitcnt lgkmcnt(14)
	s_waitcnt lgkmcnt(13)
	v_mfma_f32_32x32x16_bf16 v[0:15], v[154:157], v[70:73], v[0:15]
	s_waitcnt lgkmcnt(11)
	v_mfma_f32_32x32x16_bf16 v[16:31], v[158:161], v[70:73], v[16:31]
	v_fmamk_f32 v78, v78, 0x3e38aa3b, v234
	v_fmamk_f32 v79, v79, 0x3e38aa3b, v234
	v_fmamk_f32 v80, v80, 0x3e38aa3b, v234
	ds_read_b64_tr_b16 v[184:185], v228 offset:15360
	v_fmamk_f32 v81, v81, 0x3e38aa3b, v234
	v_fmamk_f32 v82, v82, 0x3e38aa3b, v234
	v_fmamk_f32 v83, v83, 0x3e38aa3b, v234
	v_fmamk_f32 v84, v84, 0x3e38aa3b, v234
	v_fmamk_f32 v85, v85, 0x3e38aa3b, v234
	v_exp_f32_e32 v78, v78
	v_exp_f32_e32 v79, v79
	v_exp_f32_e32 v80, v80
	v_exp_f32_e32 v81, v81
	v_exp_f32_e32 v82, v82
	v_exp_f32_e32 v83, v83
	v_exp_f32_e32 v84, v84
	v_exp_f32_e32 v85, v85
	v_add_f32_e32 v243, v243, v78
	v_add_f32_e32 v244, v244, v79
	v_add_f32_e32 v245, v245, v80
	v_add_f32_e32 v246, v246, v81
	v_add_f32_e32 v243, v243, v82
	v_add_f32_e32 v244, v244, v83
	v_add_f32_e32 v245, v245, v84
	v_add_f32_e32 v246, v246, v85
	v_cvt_pk_bf16_f32 v78, v78, v79
	v_cvt_pk_bf16_f32 v79, v80, v81
	v_cvt_pk_bf16_f32 v80, v82, v83
	v_cvt_pk_bf16_f32 v81, v84, v85
	s_waitcnt lgkmcnt(10)
	v_mfma_f32_32x32x16_bf16 v[0:15], v[162:165], v[78:81], v[0:15]
	s_waitcnt lgkmcnt(8)
	v_mfma_f32_32x32x16_bf16 v[16:31], v[166:169], v[78:81], v[16:31]
	v_fmamk_f32 v86, v86, 0x3e38aa3b, v234
	v_fmamk_f32 v87, v87, 0x3e38aa3b, v234
	v_fmamk_f32 v88, v88, 0x3e38aa3b, v234
	v_fmamk_f32 v89, v89, 0x3e38aa3b, v234
	v_fmamk_f32 v90, v90, 0x3e38aa3b, v234
	v_fmamk_f32 v91, v91, 0x3e38aa3b, v234
	v_fmamk_f32 v92, v92, 0x3e38aa3b, v234
	v_fmamk_f32 v93, v93, 0x3e38aa3b, v234
	v_exp_f32_e32 v86, v86
	v_exp_f32_e32 v87, v87
	v_exp_f32_e32 v88, v88
	v_exp_f32_e32 v89, v89
	v_exp_f32_e32 v90, v90
	v_exp_f32_e32 v91, v91
	v_exp_f32_e32 v92, v92
	v_exp_f32_e32 v93, v93
	v_add_f32_e32 v243, v243, v86
	v_add_f32_e32 v244, v244, v87
	v_add_f32_e32 v245, v245, v88
	v_add_f32_e32 v246, v246, v89
	v_add_f32_e32 v243, v243, v90
	v_add_f32_e32 v244, v244, v91
	v_add_f32_e32 v245, v245, v92
	v_add_f32_e32 v246, v246, v93
	v_cvt_pk_bf16_f32 v86, v86, v87
	v_cvt_pk_bf16_f32 v87, v88, v89
	v_cvt_pk_bf16_f32 v88, v90, v91
	v_cvt_pk_bf16_f32 v89, v92, v93
	s_waitcnt lgkmcnt(6)
	v_mfma_f32_32x32x16_bf16 v[0:15], v[170:173], v[86:89], v[0:15]
	s_waitcnt lgkmcnt(4)
	v_mfma_f32_32x32x16_bf16 v[16:31], v[174:177], v[86:89], v[16:31]
	v_fmamk_f32 v94, v94, 0x3e38aa3b, v234
	v_fmamk_f32 v95, v95, 0x3e38aa3b, v234
	v_fmamk_f32 v96, v96, 0x3e38aa3b, v234
	v_fmamk_f32 v97, v97, 0x3e38aa3b, v234
	v_fmamk_f32 v98, v98, 0x3e38aa3b, v234
	v_fmamk_f32 v99, v99, 0x3e38aa3b, v234
	v_fmamk_f32 v100, v100, 0x3e38aa3b, v234
	v_fmamk_f32 v101, v101, 0x3e38aa3b, v234
	v_exp_f32_e32 v94, v94
	v_exp_f32_e32 v95, v95
	v_exp_f32_e32 v96, v96
	v_exp_f32_e32 v97, v97
	v_exp_f32_e32 v98, v98
	v_exp_f32_e32 v99, v99
	v_exp_f32_e32 v100, v100
	v_exp_f32_e32 v101, v101
	v_add_f32_e32 v243, v243, v94
	v_add_f32_e32 v244, v244, v95
	v_add_f32_e32 v245, v245, v96
	v_add_f32_e32 v246, v246, v97
	v_add_f32_e32 v243, v243, v98
	v_add_f32_e32 v244, v244, v99
	v_add_f32_e32 v245, v245, v100
	v_add_f32_e32 v246, v246, v101
	v_cvt_pk_bf16_f32 v94, v94, v95
	v_cvt_pk_bf16_f32 v95, v96, v97
	v_cvt_pk_bf16_f32 v96, v98, v99
	v_cvt_pk_bf16_f32 v97, v100, v101
	v_add_f32_e32 v243, v243, v244
	v_add_f32_e32 v245, v245, v246
	v_add_f32_e32 v243, v243, v245
	v_fma_f32 v231, v231, v232, v243
	s_waitcnt lgkmcnt(2)
	v_mfma_f32_32x32x16_bf16 v[0:15], v[178:181], v[94:97], v[0:15]
	s_waitcnt lgkmcnt(0)
	v_mfma_f32_32x32x16_bf16 v[16:31], v[182:185], v[94:97], v[16:31]
	s_add_u32 s8, s8, 1
	s_add_u32 s18, s8, 4
	s_min_u32 s18, s18, s11
	s_mul_i32 s18, s18, 0xb2c00
	s_add_u32 s12, s4, s18
	s_addc_u32 s13, s5, 0
	s_add_u32 s19, s8, 2
	s_min_u32 s19, s19, s11
	s_mul_i32 s18, s19, 0xb2c00
	s_add_u32 s14, s4, s18
	s_addc_u32 s15, s5, 0
	s_lshl_b32 s19, s19, 3
	s_add_u32 s16, s6, s19
	s_addc_u32 s17, s7, 0
	s_cmp_lt_u32 s8, s9
	s_waitcnt vmcnt(2)
	s_barrier
	s_cbranch_scc1 .Lat_loop_2
	s_branch .Lat_epilogue
.Lat_loop_2:
	global_load_dwordx4 v[198:201], v219, s[16:17]
	s_add_i32 m0, s58, 0x4000
	s_nop 0
	global_load_lds_dwordx4 v221, s[12:13]
	s_add_i32 m0, s58, 0x8000
	s_nop 0
	global_load_lds_dwordx4 v222, s[14:15]
	s_cmp_lt_u32 s8, s10
	s_cbranch_scc1 .Lat_full_2
	s_cmp_eq_u32 s8, s10
	s_cbranch_scc1 .Lat_last_2

.Lat_nors_f2:
	v_fmamk_f32 v34, v34, 0x3e38aa3b, v234
	v_fmamk_f32 v35, v35, 0x3e38aa3b, v234
	s_waitcnt lgkmcnt(7)
	v_mfma_f32_32x32x16_bf16 v[70:85], v[118:121], v[102:105], 0
	ds_read_b64_tr_b16 v[154:155], v227 offset:16384
	ds_read_b64_tr_b16 v[156:157], v227 offset:17408
	v_fmamk_f32 v36, v36, 0x3e38aa3b, v234
	v_fmamk_f32 v37, v37, 0x3e38aa3b, v234
	v_fmamk_f32 v38, v38, 0x3e38aa3b, v234
	v_fmamk_f32 v39, v39, 0x3e38aa3b, v234
	v_fmamk_f32 v40, v40, 0x3e38aa3b, v234
	v_fmamk_f32 v41, v41, 0x3e38aa3b, v234
	v_exp_f32_e32 v34, v34
	v_exp_f32_e32 v35, v35
	v_exp_f32_e32 v36, v36
	v_exp_f32_e32 v37, v37
	v_exp_f32_e32 v38, v38
	v_exp_f32_e32 v39, v39
	s_waitcnt lgkmcnt(8)
	v_mfma_f32_32x32x16_bf16 v[86:101], v[122:125], v[102:105], 0
	ds_read_b64_tr_b16 v[158:159], v228 offset:16384
	ds_read_b64_tr_b16 v[160:161], v228 offset:17408
	v_exp_f32_e32 v40, v40
	v_exp_f32_e32 v41, v41
	v_add_f32_e32 v243, v34, v38
	v_add_f32_e32 v244, v35, v39
	v_add_f32_e32 v245, v36, v40
	v_add_f32_e32 v246, v37, v41
	v_cvt_pk_bf16_f32 v34, v34, v35
	v_cvt_pk_bf16_f32 v35, v36, v37
	v_cvt_pk_bf16_f32 v36, v38, v39
	v_cvt_pk_bf16_f32 v37, v40, v41
	v_fmamk_f32 v42, v42, 0x3e38aa3b, v234
	v_fmamk_f32 v43, v43, 0x3e38aa3b, v234
	s_waitcnt lgkmcnt(9)
	v_mfma_f32_32x32x16_bf16 v[70:85], v[126:129], v[106:109], v[70:85]
	ds_read_b64_tr_b16 v[162:163], v227 offset:18432
	ds_read_b64_tr_b16 v[164:165], v227 offset:19456
	v_fmamk_f32 v44, v44, 0x3e38aa3b, v234
	v_fmamk_f32 v45, v45, 0x3e38aa3b, v234
	v_fmamk_f32 v46, v46, 0x3e38aa3b, v234
	v_fmamk_f32 v47, v47, 0x3e38aa3b, v234
	v_fmamk_f32 v48, v48, 0x3e38aa3b, v234
	v_fmamk_f32 v49, v49, 0x3e38aa3b, v234
	v_exp_f32_e32 v42, v42
	v_exp_f32_e32 v43, v43
	v_exp_f32_e32 v44, v44
	v_exp_f32_e32 v45, v45
	v_exp_f32_e32 v46, v46
	v_exp_f32_e32 v47, v47
	s_waitcnt lgkmcnt(10)
	v_mfma_f32_32x32x16_bf16 v[86:101], v[130:133], v[106:109], v[86:101]
	ds_read_b64_tr_b16 v[166:167], v228 offset:18432
	ds_read_b64_tr_b16 v[168:169], v228 offset:19456
	v_exp_f32_e32 v48, v48
	v_exp_f32_e32 v49, v49
	v_add_f32_e32 v243, v243, v42
	v_add_f32_e32 v244, v244, v43
	v_add_f32_e32 v245, v245, v44
	v_add_f32_e32 v246, v246, v45
	v_add_f32_e32 v243, v243, v46
	v_add_f32_e32 v244, v244, v47
	v_add_f32_e32 v245, v245, v48
	v_add_f32_e32 v246, v246, v49
	v_cvt_pk_bf16_f32 v42, v42, v43
	v_cvt_pk_bf16_f32 v43, v44, v45
	s_waitcnt lgkmcnt(11)
	v_mfma_f32_32x32x16_bf16 v[70:85], v[134:137], v[110:113], v[70:85]
	ds_read_b64_tr_b16 v[170:171], v227 offset:20480
	ds_read_b64_tr_b16 v[172:173], v227 offset:21504
	v_cvt_pk_bf16_f32 v44, v46, v47
	v_cvt_pk_bf16_f32 v45, v48, v49
	v_fmamk_f32 v50, v50, 0x3e38aa3b, v234
	v_fmamk_f32 v51, v51, 0x3e38aa3b, v234
	v_fmamk_f32 v52, v52, 0x3e38aa3b, v234
	v_fmamk_f32 v53, v53, 0x3e38aa3b, v234
	v_fmamk_f32 v54, v54, 0x3e38aa3b, v234
	v_fmamk_f32 v55, v55, 0x3e38aa3b, v234
	v_fmamk_f32 v56, v56, 0x3e38aa3b, v234
	v_fmamk_f32 v57, v57, 0x3e38aa3b, v234
	v_exp_f32_e32 v50, v50
	v_exp_f32_e32 v51, v51
	s_waitcnt lgkmcnt(12)
	v_mfma_f32_32x32x16_bf16 v[86:101], v[138:141], v[110:113], v[86:101]
	ds_read_b64_tr_b16 v[174:175], v228 offset:20480
	ds_read_b64_tr_b16 v[176:177], v228 offset:21504
	v_exp_f32_e32 v52, v52
	v_exp_f32_e32 v53, v53
	v_exp_f32_e32 v54, v54
	v_exp_f32_e32 v55, v55
	v_exp_f32_e32 v56, v56
	v_exp_f32_e32 v57, v57
	v_add_f32_e32 v243, v243, v50
	v_add_f32_e32 v244, v244, v51
	v_add_f32_e32 v245, v245, v52
	v_add_f32_e32 v246, v246, v53
	v_add_f32_e32 v243, v243, v54
	v_add_f32_e32 v244, v244, v55
	s_waitcnt lgkmcnt(13)
	v_mfma_f32_32x32x16_bf16 v[70:85], v[142:145], v[114:117], v[70:85]
	ds_read_b64_tr_b16 v[178:179], v227 offset:22528
	ds_read_b64_tr_b16 v[180:181], v227 offset:23552
	v_add_f32_e32 v245, v245, v56
	v_add_f32_e32 v246, v246, v57
	v_cvt_pk_bf16_f32 v50, v50, v51
	v_cvt_pk_bf16_f32 v51, v52, v53
	v_cvt_pk_bf16_f32 v52, v54, v55
	v_cvt_pk_bf16_f32 v53, v56, v57
	v_fmamk_f32 v58, v58, 0x3e38aa3b, v234
	v_fmamk_f32 v59, v59, 0x3e38aa3b, v234
	v_fmamk_f32 v60, v60, 0x3e38aa3b, v234
	v_fmamk_f32 v61, v61, 0x3e38aa3b, v234
	v_fmamk_f32 v62, v62, 0x3e38aa3b, v234
	v_fmamk_f32 v63, v63, 0x3e38aa3b, v234
	s_waitcnt lgkmcnt(14)
	v_mfma_f32_32x32x16_bf16 v[86:101], v[146:149], v[114:117], v[86:101]
	ds_read_b64_tr_b16 v[182:183], v228 offset:22528
	ds_read_b64_tr_b16 v[184:185], v228 offset:23552
	s_waitcnt lgkmcnt(14)
	v_fmamk_f32 v64, v64, 0x3e38aa3b, v234
	v_fmamk_f32 v65, v65, 0x3e38aa3b, v234
	v_exp_f32_e32 v58, v58
	v_exp_f32_e32 v59, v59
	v_exp_f32_e32 v60, v60
	v_exp_f32_e32 v61, v61
	v_exp_f32_e32 v62, v62
	v_exp_f32_e32 v63, v63
	v_exp_f32_e32 v64, v64
	v_exp_f32_e32 v65, v65
	v_add_f32_e32 v243, v243, v58
	v_add_f32_e32 v244, v244, v59
	v_add_f32_e32 v245, v245, v60
	v_add_f32_e32 v246, v246, v61
	s_waitcnt lgkmcnt(14)
	v_mfma_f32_32x32x16_bf16 v[0:15], v[154:157], v[34:37], v[0:15]
	ds_read_b128 v[118:121], v223 offset:0
	v_add_f32_e32 v243, v243, v62
	v_add_f32_e32 v244, v244, v63
	v_add_f32_e32 v245, v245, v64
	v_add_f32_e32 v246, v246, v65
	v_cvt_pk_bf16_f32 v58, v58, v59
	v_cvt_pk_bf16_f32 v59, v60, v61
	v_cvt_pk_bf16_f32 v60, v62, v63
	v_cvt_pk_bf16_f32 v61, v64, v65
	v_add_f32_e32 v243, v243, v244
	v_add_f32_e32 v245, v245, v246
	v_add_f32_e32 v243, v243, v245
	v_fma_f32 v231, v231, v232, v243
	s_waitcnt lgkmcnt(13)
	v_mfma_f32_32x32x16_bf16 v[16:31], v[158:161], v[34:37], v[16:31]
	ds_read_b128 v[122:125], v223 offset:4096
	v_lshrrev_b32_e32 v249, v229, v204
	v_lshrrev_b32_e32 v250, v229, v205
	v_bfe_i32 v235, v249, 0, 1
	v_bfe_i32 v236, v250, 0, 1
	v_bfe_i32 v237, v249, 1, 1
	v_bfe_i32 v238, v250, 1, 1
	v_bfe_i32 v239, v249, 2, 1
	v_bfe_i32 v240, v250, 2, 1
	v_bfe_i32 v241, v249, 3, 1
	v_bfe_i32 v242, v250, 3, 1
	v_bitop3_b32 v70, v70, s33, v235 bitop3:0xe4
	s_waitcnt lgkmcnt(12)
	v_mfma_f32_32x32x16_bf16 v[0:15], v[162:165], v[42:45], v[0:15]
	ds_read_b128 v[126:129], v224 offset:0
	v_bitop3_b32 v86, v86, s33, v236 bitop3:0xe4
	v_bitop3_b32 v71, v71, s33, v237 bitop3:0xe4
	v_bitop3_b32 v87, v87, s33, v238 bitop3:0xe4
	v_bitop3_b32 v72, v72, s33, v239 bitop3:0xe4
	v_bitop3_b32 v88, v88, s33, v240 bitop3:0xe4
	v_bitop3_b32 v73, v73, s33, v241 bitop3:0xe4
	v_bitop3_b32 v89, v89, s33, v242 bitop3:0xe4
	v_max3_f32 v247, v70, s33, v86
	v_max3_f32 v248, v71, s33, v87
	v_max3_f32 v247, v247, v72, v88
	v_max3_f32 v248, v248, v73, v89
	v_bfe_i32 v235, v249, 8, 1
	s_waitcnt lgkmcnt(11)
	v_mfma_f32_32x32x16_bf16 v[16:31], v[166:169], v[42:45], v[16:31]
	ds_read_b128 v[130:133], v224 offset:4096
	v_bfe_i32 v236, v250, 8, 1
	v_bfe_i32 v237, v249, 9, 1
	v_bfe_i32 v238, v250, 9, 1
	v_bfe_i32 v239, v249, 10, 1
	v_bfe_i32 v240, v250, 10, 1
	v_bfe_i32 v241, v249, 11, 1
	v_bfe_i32 v242, v250, 11, 1
	v_bitop3_b32 v74, v74, s33, v235 bitop3:0xe4
	v_bitop3_b32 v90, v90, s33, v236 bitop3:0xe4
	v_bitop3_b32 v75, v75, s33, v237 bitop3:0xe4
	v_bitop3_b32 v91, v91, s33, v238 bitop3:0xe4
	v_bitop3_b32 v76, v76, s33, v239 bitop3:0xe4
	s_waitcnt lgkmcnt(10)
	v_mfma_f32_32x32x16_bf16 v[0:15], v[170:173], v[50:53], v[0:15]
	ds_read_b128 v[134:137], v225 offset:0
	v_bitop3_b32 v92, v92, s33, v240 bitop3:0xe4
	v_bitop3_b32 v77, v77, s33, v241 bitop3:0xe4
	v_bitop3_b32 v93, v93, s33, v242 bitop3:0xe4
	v_max3_f32 v247, v247, v74, v90
	v_max3_f32 v248, v248, v75, v91
	v_max3_f32 v247, v247, v76, v92
	v_max3_f32 v248, v248, v77, v93
	v_bfe_i32 v235, v249, 16, 1
	v_bfe_i32 v236, v250, 16, 1
	v_bfe_i32 v237, v249, 17, 1
	v_bfe_i32 v238, v250, 17, 1
	v_bfe_i32 v239, v249, 18, 1
	s_waitcnt lgkmcnt(9)
	v_mfma_f32_32x32x16_bf16 v[16:31], v[174:177], v[50:53], v[16:31]
	ds_read_b128 v[138:141], v225 offset:4096
	v_bfe_i32 v240, v250, 18, 1
	v_bfe_i32 v241, v249, 19, 1
	v_bfe_i32 v242, v250, 19, 1
	v_bitop3_b32 v78, v78, s33, v235 bitop3:0xe4
	v_bitop3_b32 v94, v94, s33, v236 bitop3:0xe4
	v_bitop3_b32 v79, v79, s33, v237 bitop3:0xe4
	v_bitop3_b32 v95, v95, s33, v238 bitop3:0xe4
	v_bitop3_b32 v80, v80, s33, v239 bitop3:0xe4
	v_bitop3_b32 v96, v96, s33, v240 bitop3:0xe4
	v_bitop3_b32 v81, v81, s33, v241 bitop3:0xe4
	v_bitop3_b32 v97, v97, s33, v242 bitop3:0xe4
	v_max3_f32 v247, v247, v78, v94
	s_waitcnt lgkmcnt(8)
	v_mfma_f32_32x32x16_bf16 v[0:15], v[178:181], v[58:61], v[0:15]
	ds_read_b128 v[142:145], v226 offset:0
	v_max3_f32 v248, v248, v79, v95
	v_max3_f32 v247, v247, v80, v96
	v_max3_f32 v248, v248, v81, v97
	v_bfe_i32 v235, v249, 24, 1
	v_bfe_i32 v236, v250, 24, 1
	v_bfe_i32 v237, v249, 25, 1
	v_bfe_i32 v238, v250, 25, 1
	v_bfe_i32 v239, v249, 26, 1
	v_bfe_i32 v240, v250, 26, 1
	v_bfe_i32 v241, v249, 27, 1
	v_bfe_i32 v242, v250, 27, 1
	v_bitop3_b32 v82, v82, s33, v235 bitop3:0xe4
	s_waitcnt lgkmcnt(7)
	v_mfma_f32_32x32x16_bf16 v[16:31], v[182:185], v[58:61], v[16:31]
	ds_read_b128 v[146:149], v226 offset:4096
	v_bitop3_b32 v98, v98, s33, v236 bitop3:0xe4
	v_bitop3_b32 v83, v83, s33, v237 bitop3:0xe4
	v_bitop3_b32 v99, v99, s33, v238 bitop3:0xe4
	v_bitop3_b32 v84, v84, s33, v239 bitop3:0xe4
	v_bitop3_b32 v100, v100, s33, v240 bitop3:0xe4
	v_bitop3_b32 v85, v85, s33, v241 bitop3:0xe4
	v_bitop3_b32 v101, v101, s33, v242 bitop3:0xe4
	v_max3_f32 v247, v247, v82, v98
	v_max3_f32 v248, v248, v83, v99
	v_max3_f32 v247, v247, v84, v100
	v_max3_f32 v248, v248, v85, v101
	v_max_f32_e32 v247, v247, v248
	v_mov_b32_e32 v248, v247
	s_nop 1
	v_permlane32_swap_b32_e32 v247, v248
	v_max3_f32 v247, v230, v247, v248
	v_cmp_neq_f32_e32 vcc, s33, v247
	s_nop 1
	v_cndmask_b32_e32 v248, 0, v247, vcc
	v_sub_f32_e32 v33, v230, v248
	v_mul_f32_e32 v33, 0x3e38aa3b, v33
	v_exp_f32_e32 v232, v33
	v_mul_f32_e32 v234, 0xbe38aa3b, v248
	v_mov_b32_e32 v230, v247
	s_add_u32 s8, s8, 1
	s_add_u32 s18, s8, 4
	s_min_u32 s18, s18, s11
	s_mul_i32 s18, s18, 0xb2c00
	s_add_u32 s12, s4, s18
	s_addc_u32 s13, s5, 0
	s_add_u32 s19, s8, 2
	s_min_u32 s19, s19, s11
	s_mul_i32 s18, s19, 0xb2c00
	s_add_u32 s14, s4, s18
	s_addc_u32 s15, s5, 0
	s_cmp_lt_u32 s8, s9
	s_waitcnt vmcnt(3)
	s_barrier
	s_cbranch_scc1 .Lat_loop_3
	s_branch .Lat_epilogue

.Lat_nors_l2:
	v_fmamk_f32 v34, v34, 0x3e38aa3b, v234
	v_fmamk_f32 v35, v35, 0x3e38aa3b, v234
	v_fmamk_f32 v36, v36, 0x3e38aa3b, v234
	ds_read_b64_tr_b16 v[168:169], v228 offset:19456
	s_waitcnt lgkmcnt(14)
	v_fmamk_f32 v37, v37, 0x3e38aa3b, v234
	v_fmamk_f32 v38, v38, 0x3e38aa3b, v234
	v_fmamk_f32 v39, v39, 0x3e38aa3b, v234
	ds_read_b64_tr_b16 v[170:171], v227 offset:20480
	s_waitcnt lgkmcnt(14)
	v_fmamk_f32 v40, v40, 0x3e38aa3b, v234
	v_fmamk_f32 v41, v41, 0x3e38aa3b, v234
	v_exp_f32_e32 v34, v34
	ds_read_b64_tr_b16 v[172:173], v227 offset:21504
	s_waitcnt lgkmcnt(14)
	v_exp_f32_e32 v35, v35
	v_exp_f32_e32 v36, v36
	v_exp_f32_e32 v37, v37
	ds_read_b64_tr_b16 v[174:175], v228 offset:20480
	s_waitcnt lgkmcnt(14)
	v_exp_f32_e32 v38, v38
	v_exp_f32_e32 v39, v39
	v_exp_f32_e32 v40, v40
	ds_read_b64_tr_b16 v[176:177], v228 offset:21504
	s_waitcnt lgkmcnt(14)
	v_exp_f32_e32 v41, v41
	v_add_f32_e32 v243, v34, v38
	v_add_f32_e32 v244, v35, v39
	ds_read_b64_tr_b16 v[178:179], v227 offset:22528
	s_waitcnt lgkmcnt(14)
	v_add_f32_e32 v245, v36, v40
	v_add_f32_e32 v246, v37, v41
	v_cvt_pk_bf16_f32 v34, v34, v35
	ds_read_b64_tr_b16 v[180:181], v227 offset:23552
	s_waitcnt lgkmcnt(14)
	v_cvt_pk_bf16_f32 v35, v36, v37
	v_cvt_pk_bf16_f32 v36, v38, v39
	v_cvt_pk_bf16_f32 v37, v40, v41
	ds_read_b64_tr_b16 v[182:183], v228 offset:22528
	s_waitcnt lgkmcnt(14)
	s_waitcnt lgkmcnt(13)
	v_mfma_f32_32x32x16_bf16 v[0:15], v[154:157], v[34:37], v[0:15]
	s_waitcnt lgkmcnt(11)
	v_mfma_f32_32x32x16_bf16 v[16:31], v[158:161], v[34:37], v[16:31]
	v_fmamk_f32 v42, v42, 0x3e38aa3b, v234
	v_fmamk_f32 v43, v43, 0x3e38aa3b, v234
	v_fmamk_f32 v44, v44, 0x3e38aa3b, v234
	ds_read_b64_tr_b16 v[184:185], v228 offset:23552
	v_fmamk_f32 v45, v45, 0x3e38aa3b, v234
	v_fmamk_f32 v46, v46, 0x3e38aa3b, v234
	v_fmamk_f32 v47, v47, 0x3e38aa3b, v234
	v_fmamk_f32 v48, v48, 0x3e38aa3b, v234
	v_fmamk_f32 v49, v49, 0x3e38aa3b, v234
	v_exp_f32_e32 v42, v42
	v_exp_f32_e32 v43, v43
	v_exp_f32_e32 v44, v44
	v_exp_f32_e32 v45, v45
	v_exp_f32_e32 v46, v46
	v_exp_f32_e32 v47, v47
	v_exp_f32_e32 v48, v48
	v_exp_f32_e32 v49, v49
	v_add_f32_e32 v243, v243, v42
	v_add_f32_e32 v244, v244, v43
	v_add_f32_e32 v245, v245, v44
	v_add_f32_e32 v246, v246, v45
	v_add_f32_e32 v243, v243, v46
	v_add_f32_e32 v244, v244, v47
	v_add_f32_e32 v245, v245, v48
	v_add_f32_e32 v246, v246, v49
	v_cvt_pk_bf16_f32 v42, v42, v43
	v_cvt_pk_bf16_f32 v43, v44, v45
	v_cvt_pk_bf16_f32 v44, v46, v47
	v_cvt_pk_bf16_f32 v45, v48, v49
	s_waitcnt lgkmcnt(10)
	v_mfma_f32_32x32x16_bf16 v[0:15], v[162:165], v[42:45], v[0:15]
	s_waitcnt lgkmcnt(8)
	v_mfma_f32_32x32x16_bf16 v[16:31], v[166:169], v[42:45], v[16:31]
	v_fmamk_f32 v50, v50, 0x3e38aa3b, v234
	v_fmamk_f32 v51, v51, 0x3e38aa3b, v234
	v_fmamk_f32 v52, v52, 0x3e38aa3b, v234
	v_fmamk_f32 v53, v53, 0x3e38aa3b, v234
	v_fmamk_f32 v54, v54, 0x3e38aa3b, v234
	v_fmamk_f32 v55, v55, 0x3e38aa3b, v234
	v_fmamk_f32 v56, v56, 0x3e38aa3b, v234
	v_fmamk_f32 v57, v57, 0x3e38aa3b, v234
	v_exp_f32_e32 v50, v50
	v_exp_f32_e32 v51, v51
	v_exp_f32_e32 v52, v52
	v_exp_f32_e32 v53, v53
	v_exp_f32_e32 v54, v54
	v_exp_f32_e32 v55, v55
	v_exp_f32_e32 v56, v56
	v_exp_f32_e32 v57, v57
	v_add_f32_e32 v243, v243, v50
	v_add_f32_e32 v244, v244, v51
	v_add_f32_e32 v245, v245, v52
	v_add_f32_e32 v246, v246, v53
	v_add_f32_e32 v243, v243, v54
	v_add_f32_e32 v244, v244, v55
	v_add_f32_e32 v245, v245, v56
	v_add_f32_e32 v246, v246, v57
	v_cvt_pk_bf16_f32 v50, v50, v51
	v_cvt_pk_bf16_f32 v51, v52, v53
	v_cvt_pk_bf16_f32 v52, v54, v55
	v_cvt_pk_bf16_f32 v53, v56, v57
	s_waitcnt lgkmcnt(6)
	v_mfma_f32_32x32x16_bf16 v[0:15], v[170:173], v[50:53], v[0:15]
	s_waitcnt lgkmcnt(4)
	v_mfma_f32_32x32x16_bf16 v[16:31], v[174:177], v[50:53], v[16:31]
	v_fmamk_f32 v58, v58, 0x3e38aa3b, v234
	v_fmamk_f32 v59, v59, 0x3e38aa3b, v234
	v_fmamk_f32 v60, v60, 0x3e38aa3b, v234
	v_fmamk_f32 v61, v61, 0x3e38aa3b, v234
	v_fmamk_f32 v62, v62, 0x3e38aa3b, v234
	v_fmamk_f32 v63, v63, 0x3e38aa3b, v234
	v_fmamk_f32 v64, v64, 0x3e38aa3b, v234
	v_fmamk_f32 v65, v65, 0x3e38aa3b, v234
	v_exp_f32_e32 v58, v58
	v_exp_f32_e32 v59, v59
	v_exp_f32_e32 v60, v60
	v_exp_f32_e32 v61, v61
	v_exp_f32_e32 v62, v62
	v_exp_f32_e32 v63, v63
	v_exp_f32_e32 v64, v64
	v_exp_f32_e32 v65, v65
	v_add_f32_e32 v243, v243, v58
	v_add_f32_e32 v244, v244, v59
	v_add_f32_e32 v245, v245, v60
	v_add_f32_e32 v246, v246, v61
	v_add_f32_e32 v243, v243, v62
	v_add_f32_e32 v244, v244, v63
	v_add_f32_e32 v245, v245, v64
	v_add_f32_e32 v246, v246, v65
	v_cvt_pk_bf16_f32 v58, v58, v59
	v_cvt_pk_bf16_f32 v59, v60, v61
	v_cvt_pk_bf16_f32 v60, v62, v63
	v_cvt_pk_bf16_f32 v61, v64, v65
	v_add_f32_e32 v243, v243, v244
	v_add_f32_e32 v245, v245, v246
	v_add_f32_e32 v243, v243, v245
	v_fma_f32 v231, v231, v232, v243
	s_waitcnt lgkmcnt(2)
	v_mfma_f32_32x32x16_bf16 v[0:15], v[178:181], v[58:61], v[0:15]
	s_waitcnt lgkmcnt(0)
	v_mfma_f32_32x32x16_bf16 v[16:31], v[182:185], v[58:61], v[16:31]
	s_add_u32 s8, s8, 1
	s_add_u32 s18, s8, 4
	s_min_u32 s18, s18, s11
	s_mul_i32 s18, s18, 0xb2c00
	s_add_u32 s12, s4, s18
	s_addc_u32 s13, s5, 0
	s_add_u32 s19, s8, 2
	s_min_u32 s19, s19, s11
	s_mul_i32 s18, s19, 0xb2c00
	s_add_u32 s14, s4, s18
	s_addc_u32 s15, s5, 0
	s_cmp_lt_u32 s8, s9
	s_waitcnt vmcnt(3)
	s_barrier
	s_cbranch_scc1 .Lat_loop_3
	s_branch .Lat_epilogue
.Lat_loop_3:
	s_add_i32 m0, s58, 0x6000
	s_nop 0
	global_load_lds_dwordx4 v221, s[12:13]
	s_add_i32 m0, s58, 0xa000
	s_nop 0
	global_load_lds_dwordx4 v222, s[14:15]
	s_cmp_lt_u32 s8, s10
	s_cbranch_scc1 .Lat_full_3
	s_cmp_eq_u32 s8, s10
	s_cbranch_scc1 .Lat_last_3

.Lat_nors_f3:
	v_fmamk_f32 v70, v70, 0x3e38aa3b, v234
	v_fmamk_f32 v71, v71, 0x3e38aa3b, v234
	s_waitcnt lgkmcnt(7)
	v_mfma_f32_32x32x16_bf16 v[34:49], v[118:121], v[102:105], 0
	ds_read_b64_tr_b16 v[154:155], v227 offset:24576
	ds_read_b64_tr_b16 v[156:157], v227 offset:25600
	v_fmamk_f32 v72, v72, 0x3e38aa3b, v234
	v_fmamk_f32 v73, v73, 0x3e38aa3b, v234
	v_fmamk_f32 v74, v74, 0x3e38aa3b, v234
	v_fmamk_f32 v75, v75, 0x3e38aa3b, v234
	v_fmamk_f32 v76, v76, 0x3e38aa3b, v234
	v_fmamk_f32 v77, v77, 0x3e38aa3b, v234
	v_exp_f32_e32 v70, v70
	v_exp_f32_e32 v71, v71
	v_exp_f32_e32 v72, v72
	v_exp_f32_e32 v73, v73
	v_exp_f32_e32 v74, v74
	v_exp_f32_e32 v75, v75
	s_waitcnt lgkmcnt(8)
	v_mfma_f32_32x32x16_bf16 v[50:65], v[122:125], v[102:105], 0
	ds_read_b64_tr_b16 v[158:159], v228 offset:24576
	ds_read_b64_tr_b16 v[160:161], v228 offset:25600
	v_exp_f32_e32 v76, v76
	v_exp_f32_e32 v77, v77
	v_add_f32_e32 v243, v70, v74
	v_add_f32_e32 v244, v71, v75
	v_add_f32_e32 v245, v72, v76
	v_add_f32_e32 v246, v73, v77
	v_cvt_pk_bf16_f32 v70, v70, v71
	v_cvt_pk_bf16_f32 v71, v72, v73
	v_cvt_pk_bf16_f32 v72, v74, v75
	v_cvt_pk_bf16_f32 v73, v76, v77
	v_fmamk_f32 v78, v78, 0x3e38aa3b, v234
	v_fmamk_f32 v79, v79, 0x3e38aa3b, v234
	s_waitcnt lgkmcnt(9)
	v_mfma_f32_32x32x16_bf16 v[34:49], v[126:129], v[106:109], v[34:49]
	ds_read_b64_tr_b16 v[162:163], v227 offset:26624
	ds_read_b64_tr_b16 v[164:165], v227 offset:27648
	v_fmamk_f32 v80, v80, 0x3e38aa3b, v234
	v_fmamk_f32 v81, v81, 0x3e38aa3b, v234
	v_fmamk_f32 v82, v82, 0x3e38aa3b, v234
	v_fmamk_f32 v83, v83, 0x3e38aa3b, v234
	v_fmamk_f32 v84, v84, 0x3e38aa3b, v234
	v_fmamk_f32 v85, v85, 0x3e38aa3b, v234
	v_exp_f32_e32 v78, v78
	v_exp_f32_e32 v79, v79
	v_exp_f32_e32 v80, v80
	v_exp_f32_e32 v81, v81
	v_exp_f32_e32 v82, v82
	v_exp_f32_e32 v83, v83
	s_waitcnt lgkmcnt(10)
	v_mfma_f32_32x32x16_bf16 v[50:65], v[130:133], v[106:109], v[50:65]
	ds_read_b64_tr_b16 v[166:167], v228 offset:26624
	ds_read_b64_tr_b16 v[168:169], v228 offset:27648
	v_exp_f32_e32 v84, v84
	v_exp_f32_e32 v85, v85
	v_add_f32_e32 v243, v243, v78
	v_add_f32_e32 v244, v244, v79
	v_add_f32_e32 v245, v245, v80
	v_add_f32_e32 v246, v246, v81
	v_add_f32_e32 v243, v243, v82
	v_add_f32_e32 v244, v244, v83
	v_add_f32_e32 v245, v245, v84
	v_add_f32_e32 v246, v246, v85
	v_cvt_pk_bf16_f32 v78, v78, v79
	v_cvt_pk_bf16_f32 v79, v80, v81
	s_waitcnt lgkmcnt(11)
	v_mfma_f32_32x32x16_bf16 v[34:49], v[134:137], v[110:113], v[34:49]
	ds_read_b64_tr_b16 v[170:171], v227 offset:28672
	ds_read_b64_tr_b16 v[172:173], v227 offset:29696
	v_cvt_pk_bf16_f32 v80, v82, v83
	v_cvt_pk_bf16_f32 v81, v84, v85
	v_fmamk_f32 v86, v86, 0x3e38aa3b, v234
	v_fmamk_f32 v87, v87, 0x3e38aa3b, v234
	v_fmamk_f32 v88, v88, 0x3e38aa3b, v234
	v_fmamk_f32 v89, v89, 0x3e38aa3b, v234
	v_fmamk_f32 v90, v90, 0x3e38aa3b, v234
	v_fmamk_f32 v91, v91, 0x3e38aa3b, v234
	v_fmamk_f32 v92, v92, 0x3e38aa3b, v234
	v_fmamk_f32 v93, v93, 0x3e38aa3b, v234
	v_exp_f32_e32 v86, v86
	v_exp_f32_e32 v87, v87
	s_waitcnt lgkmcnt(12)
	v_mfma_f32_32x32x16_bf16 v[50:65], v[138:141], v[110:113], v[50:65]
	ds_read_b64_tr_b16 v[174:175], v228 offset:28672
	ds_read_b64_tr_b16 v[176:177], v228 offset:29696
	v_exp_f32_e32 v88, v88
	v_exp_f32_e32 v89, v89
	v_exp_f32_e32 v90, v90
	v_exp_f32_e32 v91, v91
	v_exp_f32_e32 v92, v92
	v_exp_f32_e32 v93, v93
	v_add_f32_e32 v243, v243, v86
	v_add_f32_e32 v244, v244, v87
	v_add_f32_e32 v245, v245, v88
	v_add_f32_e32 v246, v246, v89
	v_add_f32_e32 v243, v243, v90
	v_add_f32_e32 v244, v244, v91
	s_waitcnt lgkmcnt(13)
	v_mfma_f32_32x32x16_bf16 v[34:49], v[142:145], v[114:117], v[34:49]
	ds_read_b64_tr_b16 v[178:179], v227 offset:30720
	ds_read_b64_tr_b16 v[180:181], v227 offset:31744
	v_add_f32_e32 v245, v245, v92
	v_add_f32_e32 v246, v246, v93
	v_cvt_pk_bf16_f32 v86, v86, v87
	v_cvt_pk_bf16_f32 v87, v88, v89
	v_cvt_pk_bf16_f32 v88, v90, v91
	v_cvt_pk_bf16_f32 v89, v92, v93
	v_fmamk_f32 v94, v94, 0x3e38aa3b, v234
	v_fmamk_f32 v95, v95, 0x3e38aa3b, v234
	v_fmamk_f32 v96, v96, 0x3e38aa3b, v234
	v_fmamk_f32 v97, v97, 0x3e38aa3b, v234
	v_fmamk_f32 v98, v98, 0x3e38aa3b, v234
	v_fmamk_f32 v99, v99, 0x3e38aa3b, v234
	s_waitcnt lgkmcnt(14)
	v_mfma_f32_32x32x16_bf16 v[50:65], v[146:149], v[114:117], v[50:65]
	ds_read_b64_tr_b16 v[182:183], v228 offset:30720
	ds_read_b64_tr_b16 v[184:185], v228 offset:31744
	s_waitcnt lgkmcnt(14)
	v_fmamk_f32 v100, v100, 0x3e38aa3b, v234
	v_fmamk_f32 v101, v101, 0x3e38aa3b, v234
	v_exp_f32_e32 v94, v94
	v_exp_f32_e32 v95, v95
	v_exp_f32_e32 v96, v96
	v_exp_f32_e32 v97, v97
	v_exp_f32_e32 v98, v98
	v_exp_f32_e32 v99, v99
	v_exp_f32_e32 v100, v100
	v_exp_f32_e32 v101, v101
	v_add_f32_e32 v243, v243, v94
	v_add_f32_e32 v244, v244, v95
	v_add_f32_e32 v245, v245, v96
	v_add_f32_e32 v246, v246, v97
	s_waitcnt lgkmcnt(14)
	v_mfma_f32_32x32x16_bf16 v[0:15], v[154:157], v[70:73], v[0:15]
	ds_read_b128 v[118:121], v223 offset:8192
	v_add_f32_e32 v243, v243, v98
	v_add_f32_e32 v244, v244, v99
	v_add_f32_e32 v245, v245, v100
	v_add_f32_e32 v246, v246, v101
	v_cvt_pk_bf16_f32 v94, v94, v95
	v_cvt_pk_bf16_f32 v95, v96, v97
	v_cvt_pk_bf16_f32 v96, v98, v99
	v_cvt_pk_bf16_f32 v97, v100, v101
	v_add_f32_e32 v243, v243, v244
	v_add_f32_e32 v245, v245, v246
	v_add_f32_e32 v243, v243, v245
	v_fma_f32 v231, v231, v232, v243
	s_waitcnt lgkmcnt(13)
	v_mfma_f32_32x32x16_bf16 v[16:31], v[158:161], v[70:73], v[16:31]
	ds_read_b128 v[122:125], v223 offset:12288
	s_waitcnt vmcnt(4)
	v_lshrrev_b32_e32 v249, v229, v198
	v_lshrrev_b32_e32 v250, v229, v199
	v_bfe_i32 v235, v249, 0, 1
	v_bfe_i32 v236, v250, 0, 1
	v_bfe_i32 v237, v249, 1, 1
	v_bfe_i32 v238, v250, 1, 1
	v_bfe_i32 v239, v249, 2, 1
	v_bfe_i32 v240, v250, 2, 1
	v_bfe_i32 v241, v249, 3, 1
	v_bfe_i32 v242, v250, 3, 1
	v_bitop3_b32 v34, v34, s33, v235 bitop3:0xe4
	s_waitcnt lgkmcnt(12)
	v_mfma_f32_32x32x16_bf16 v[0:15], v[162:165], v[78:81], v[0:15]
	ds_read_b128 v[126:129], v224 offset:8192
	v_bitop3_b32 v50, v50, s33, v236 bitop3:0xe4
	v_bitop3_b32 v35, v35, s33, v237 bitop3:0xe4
	v_bitop3_b32 v51, v51, s33, v238 bitop3:0xe4
	v_bitop3_b32 v36, v36, s33, v239 bitop3:0xe4
	v_bitop3_b32 v52, v52, s33, v240 bitop3:0xe4
	v_bitop3_b32 v37, v37, s33, v241 bitop3:0xe4
	v_bitop3_b32 v53, v53, s33, v242 bitop3:0xe4
	v_max3_f32 v247, v34, s33, v50
	v_max3_f32 v248, v35, s33, v51
	v_max3_f32 v247, v247, v36, v52
	v_max3_f32 v248, v248, v37, v53
	v_bfe_i32 v235, v249, 8, 1
	s_waitcnt lgkmcnt(11)
	v_mfma_f32_32x32x16_bf16 v[16:31], v[166:169], v[78:81], v[16:31]
	ds_read_b128 v[130:133], v224 offset:12288
	v_bfe_i32 v236, v250, 8, 1
	v_bfe_i32 v237, v249, 9, 1
	v_bfe_i32 v238, v250, 9, 1
	v_bfe_i32 v239, v249, 10, 1
	v_bfe_i32 v240, v250, 10, 1
	v_bfe_i32 v241, v249, 11, 1
	v_bfe_i32 v242, v250, 11, 1
	v_bitop3_b32 v38, v38, s33, v235 bitop3:0xe4
	v_bitop3_b32 v54, v54, s33, v236 bitop3:0xe4
	v_bitop3_b32 v39, v39, s33, v237 bitop3:0xe4
	v_bitop3_b32 v55, v55, s33, v238 bitop3:0xe4
	v_bitop3_b32 v40, v40, s33, v239 bitop3:0xe4
	s_waitcnt lgkmcnt(10)
	v_mfma_f32_32x32x16_bf16 v[0:15], v[170:173], v[86:89], v[0:15]
	ds_read_b128 v[134:137], v225 offset:8192
	v_bitop3_b32 v56, v56, s33, v240 bitop3:0xe4
	v_bitop3_b32 v41, v41, s33, v241 bitop3:0xe4
	v_bitop3_b32 v57, v57, s33, v242 bitop3:0xe4
	v_max3_f32 v247, v247, v38, v54
	v_max3_f32 v248, v248, v39, v55
	v_max3_f32 v247, v247, v40, v56
	v_max3_f32 v248, v248, v41, v57
	v_bfe_i32 v235, v249, 16, 1
	v_bfe_i32 v236, v250, 16, 1
	v_bfe_i32 v237, v249, 17, 1
	v_bfe_i32 v238, v250, 17, 1
	v_bfe_i32 v239, v249, 18, 1
	s_waitcnt lgkmcnt(9)
	v_mfma_f32_32x32x16_bf16 v[16:31], v[174:177], v[86:89], v[16:31]
	ds_read_b128 v[138:141], v225 offset:12288
	v_bfe_i32 v240, v250, 18, 1
	v_bfe_i32 v241, v249, 19, 1
	v_bfe_i32 v242, v250, 19, 1
	v_bitop3_b32 v42, v42, s33, v235 bitop3:0xe4
	v_bitop3_b32 v58, v58, s33, v236 bitop3:0xe4
	v_bitop3_b32 v43, v43, s33, v237 bitop3:0xe4
	v_bitop3_b32 v59, v59, s33, v238 bitop3:0xe4
	v_bitop3_b32 v44, v44, s33, v239 bitop3:0xe4
	v_bitop3_b32 v60, v60, s33, v240 bitop3:0xe4
	v_bitop3_b32 v45, v45, s33, v241 bitop3:0xe4
	v_bitop3_b32 v61, v61, s33, v242 bitop3:0xe4
	v_max3_f32 v247, v247, v42, v58
	s_waitcnt lgkmcnt(8)
	v_mfma_f32_32x32x16_bf16 v[0:15], v[178:181], v[94:97], v[0:15]
	ds_read_b128 v[142:145], v226 offset:8192
	v_max3_f32 v248, v248, v43, v59
	v_max3_f32 v247, v247, v44, v60
	v_max3_f32 v248, v248, v45, v61
	v_bfe_i32 v235, v249, 24, 1
	v_bfe_i32 v236, v250, 24, 1
	v_bfe_i32 v237, v249, 25, 1
	v_bfe_i32 v238, v250, 25, 1
	v_bfe_i32 v239, v249, 26, 1
	v_bfe_i32 v240, v250, 26, 1
	v_bfe_i32 v241, v249, 27, 1
	v_bfe_i32 v242, v250, 27, 1
	v_bitop3_b32 v46, v46, s33, v235 bitop3:0xe4
	s_waitcnt lgkmcnt(7)
	v_mfma_f32_32x32x16_bf16 v[16:31], v[182:185], v[94:97], v[16:31]
	ds_read_b128 v[146:149], v226 offset:12288
	v_bitop3_b32 v62, v62, s33, v236 bitop3:0xe4
	v_bitop3_b32 v47, v47, s33, v237 bitop3:0xe4
	v_bitop3_b32 v63, v63, s33, v238 bitop3:0xe4
	v_bitop3_b32 v48, v48, s33, v239 bitop3:0xe4
	v_bitop3_b32 v64, v64, s33, v240 bitop3:0xe4
	v_bitop3_b32 v49, v49, s33, v241 bitop3:0xe4
	v_bitop3_b32 v65, v65, s33, v242 bitop3:0xe4
	v_max3_f32 v247, v247, v46, v62
	v_max3_f32 v248, v248, v47, v63
	v_max3_f32 v247, v247, v48, v64
	v_max3_f32 v248, v248, v49, v65
	v_max_f32_e32 v247, v247, v248
	v_mov_b32_e32 v248, v247
	s_nop 1
	v_permlane32_swap_b32_e32 v247, v248
	v_max3_f32 v247, v230, v247, v248
	v_cmp_neq_f32_e32 vcc, s33, v247
	s_nop 1
	v_cndmask_b32_e32 v248, 0, v247, vcc
	v_sub_f32_e32 v33, v230, v248
	v_mul_f32_e32 v33, 0x3e38aa3b, v33
	v_exp_f32_e32 v232, v33
	v_mul_f32_e32 v234, 0xbe38aa3b, v248
	v_mov_b32_e32 v230, v247
	s_add_u32 s8, s8, 1
	s_add_u32 s18, s8, 4
	s_min_u32 s18, s18, s11
	s_mul_i32 s18, s18, 0xb2c00
	s_add_u32 s12, s4, s18
	s_addc_u32 s13, s5, 0
	s_add_u32 s19, s8, 2
	s_min_u32 s19, s19, s11
	s_mul_i32 s18, s19, 0xb2c00
	s_add_u32 s14, s4, s18
	s_addc_u32 s15, s5, 0
	s_lshl_b32 s19, s19, 3
	s_add_u32 s16, s6, s19
	s_addc_u32 s17, s7, 0
	s_cmp_lt_u32 s8, s9
	s_waitcnt vmcnt(2)
	s_barrier
	s_cbranch_scc1 .Lat_loop_0
	s_branch .Lat_epilogue

.Lat_nors_l3:
	v_fmamk_f32 v70, v70, 0x3e38aa3b, v234
	v_fmamk_f32 v71, v71, 0x3e38aa3b, v234
	v_fmamk_f32 v72, v72, 0x3e38aa3b, v234
	ds_read_b64_tr_b16 v[168:169], v228 offset:27648
	s_waitcnt lgkmcnt(14)
	v_fmamk_f32 v73, v73, 0x3e38aa3b, v234
	v_fmamk_f32 v74, v74, 0x3e38aa3b, v234
	v_fmamk_f32 v75, v75, 0x3e38aa3b, v234
	ds_read_b64_tr_b16 v[170:171], v227 offset:28672
	s_waitcnt lgkmcnt(14)
	v_fmamk_f32 v76, v76, 0x3e38aa3b, v234
	v_fmamk_f32 v77, v77, 0x3e38aa3b, v234
	v_exp_f32_e32 v70, v70
	ds_read_b64_tr_b16 v[172:173], v227 offset:29696
	s_waitcnt lgkmcnt(14)
	v_exp_f32_e32 v71, v71
	v_exp_f32_e32 v72, v72
	v_exp_f32_e32 v73, v73
	ds_read_b64_tr_b16 v[174:175], v228 offset:28672
	s_waitcnt lgkmcnt(14)
	v_exp_f32_e32 v74, v74
	v_exp_f32_e32 v75, v75
	v_exp_f32_e32 v76, v76
	ds_read_b64_tr_b16 v[176:177], v228 offset:29696
	s_waitcnt lgkmcnt(14)
	v_exp_f32_e32 v77, v77
	v_add_f32_e32 v243, v70, v74
	v_add_f32_e32 v244, v71, v75
	ds_read_b64_tr_b16 v[178:179], v227 offset:30720
	s_waitcnt lgkmcnt(14)
	v_add_f32_e32 v245, v72, v76
	v_add_f32_e32 v246, v73, v77
	v_cvt_pk_bf16_f32 v70, v70, v71
	ds_read_b64_tr_b16 v[180:181], v227 offset:31744
	s_waitcnt lgkmcnt(14)
	v_cvt_pk_bf16_f32 v71, v72, v73
	v_cvt_pk_bf16_f32 v72, v74, v75
	v_cvt_pk_bf16_f32 v73, v76, v77
	ds_read_b64_tr_b16 v[182:183], v228 offset:30720
	s_waitcnt lgkmcnt(14)
	s_waitcnt lgkmcnt(13)
	v_mfma_f32_32x32x16_bf16 v[0:15], v[154:157], v[70:73], v[0:15]
	s_waitcnt lgkmcnt(11)
	v_mfma_f32_32x32x16_bf16 v[16:31], v[158:161], v[70:73], v[16:31]
	v_fmamk_f32 v78, v78, 0x3e38aa3b, v234
	v_fmamk_f32 v79, v79, 0x3e38aa3b, v234
	v_fmamk_f32 v80, v80, 0x3e38aa3b, v234
	ds_read_b64_tr_b16 v[184:185], v228 offset:31744
	v_fmamk_f32 v81, v81, 0x3e38aa3b, v234
	v_fmamk_f32 v82, v82, 0x3e38aa3b, v234
	v_fmamk_f32 v83, v83, 0x3e38aa3b, v234
	v_fmamk_f32 v84, v84, 0x3e38aa3b, v234
	v_fmamk_f32 v85, v85, 0x3e38aa3b, v234
	v_exp_f32_e32 v78, v78
	v_exp_f32_e32 v79, v79
	v_exp_f32_e32 v80, v80
	v_exp_f32_e32 v81, v81
	v_exp_f32_e32 v82, v82
	v_exp_f32_e32 v83, v83
	v_exp_f32_e32 v84, v84
	v_exp_f32_e32 v85, v85
	v_add_f32_e32 v243, v243, v78
	v_add_f32_e32 v244, v244, v79
	v_add_f32_e32 v245, v245, v80
	v_add_f32_e32 v246, v246, v81
	v_add_f32_e32 v243, v243, v82
	v_add_f32_e32 v244, v244, v83
	v_add_f32_e32 v245, v245, v84
	v_add_f32_e32 v246, v246, v85
	v_cvt_pk_bf16_f32 v78, v78, v79
	v_cvt_pk_bf16_f32 v79, v80, v81
	v_cvt_pk_bf16_f32 v80, v82, v83
	v_cvt_pk_bf16_f32 v81, v84, v85
	s_waitcnt lgkmcnt(10)
	v_mfma_f32_32x32x16_bf16 v[0:15], v[162:165], v[78:81], v[0:15]
	s_waitcnt lgkmcnt(8)
	v_mfma_f32_32x32x16_bf16 v[16:31], v[166:169], v[78:81], v[16:31]
	v_fmamk_f32 v86, v86, 0x3e38aa3b, v234
	v_fmamk_f32 v87, v87, 0x3e38aa3b, v234
	v_fmamk_f32 v88, v88, 0x3e38aa3b, v234
	v_fmamk_f32 v89, v89, 0x3e38aa3b, v234
	v_fmamk_f32 v90, v90, 0x3e38aa3b, v234
	v_fmamk_f32 v91, v91, 0x3e38aa3b, v234
	v_fmamk_f32 v92, v92, 0x3e38aa3b, v234
	v_fmamk_f32 v93, v93, 0x3e38aa3b, v234
	v_exp_f32_e32 v86, v86
	v_exp_f32_e32 v87, v87
	v_exp_f32_e32 v88, v88
	v_exp_f32_e32 v89, v89
	v_exp_f32_e32 v90, v90
	v_exp_f32_e32 v91, v91
	v_exp_f32_e32 v92, v92
	v_exp_f32_e32 v93, v93
	v_add_f32_e32 v243, v243, v86
	v_add_f32_e32 v244, v244, v87
	v_add_f32_e32 v245, v245, v88
	v_add_f32_e32 v246, v246, v89
	v_add_f32_e32 v243, v243, v90
	v_add_f32_e32 v244, v244, v91
	v_add_f32_e32 v245, v245, v92
	v_add_f32_e32 v246, v246, v93
	v_cvt_pk_bf16_f32 v86, v86, v87
	v_cvt_pk_bf16_f32 v87, v88, v89
	v_cvt_pk_bf16_f32 v88, v90, v91
	v_cvt_pk_bf16_f32 v89, v92, v93
	s_waitcnt lgkmcnt(6)
	v_mfma_f32_32x32x16_bf16 v[0:15], v[170:173], v[86:89], v[0:15]
	s_waitcnt lgkmcnt(4)
	v_mfma_f32_32x32x16_bf16 v[16:31], v[174:177], v[86:89], v[16:31]
	v_fmamk_f32 v94, v94, 0x3e38aa3b, v234
	v_fmamk_f32 v95, v95, 0x3e38aa3b, v234
	v_fmamk_f32 v96, v96, 0x3e38aa3b, v234
	v_fmamk_f32 v97, v97, 0x3e38aa3b, v234
	v_fmamk_f32 v98, v98, 0x3e38aa3b, v234
	v_fmamk_f32 v99, v99, 0x3e38aa3b, v234
	v_fmamk_f32 v100, v100, 0x3e38aa3b, v234
	v_fmamk_f32 v101, v101, 0x3e38aa3b, v234
	v_exp_f32_e32 v94, v94
	v_exp_f32_e32 v95, v95
	v_exp_f32_e32 v96, v96
	v_exp_f32_e32 v97, v97
	v_exp_f32_e32 v98, v98
	v_exp_f32_e32 v99, v99
	v_exp_f32_e32 v100, v100
	v_exp_f32_e32 v101, v101
	v_add_f32_e32 v243, v243, v94
	v_add_f32_e32 v244, v244, v95
	v_add_f32_e32 v245, v245, v96
	v_add_f32_e32 v246, v246, v97
	v_add_f32_e32 v243, v243, v98
	v_add_f32_e32 v244, v244, v99
	v_add_f32_e32 v245, v245, v100
	v_add_f32_e32 v246, v246, v101
	v_cvt_pk_bf16_f32 v94, v94, v95
	v_cvt_pk_bf16_f32 v95, v96, v97
	v_cvt_pk_bf16_f32 v96, v98, v99
	v_cvt_pk_bf16_f32 v97, v100, v101
	v_add_f32_e32 v243, v243, v244
	v_add_f32_e32 v245, v245, v246
	v_add_f32_e32 v243, v243, v245
	v_fma_f32 v231, v231, v232, v243
	s_waitcnt lgkmcnt(2)
	v_mfma_f32_32x32x16_bf16 v[0:15], v[178:181], v[94:97], v[0:15]
	s_waitcnt lgkmcnt(0)
	v_mfma_f32_32x32x16_bf16 v[16:31], v[182:185], v[94:97], v[16:31]
	s_add_u32 s8, s8, 1
	s_add_u32 s18, s8, 4
	s_min_u32 s18, s18, s11
	s_mul_i32 s18, s18, 0xb2c00
	s_add_u32 s12, s4, s18
	s_addc_u32 s13, s5, 0
	s_add_u32 s19, s8, 2
	s_min_u32 s19, s19, s11
	s_mul_i32 s18, s19, 0xb2c00
	s_add_u32 s14, s4, s18
	s_addc_u32 s15, s5, 0
	s_lshl_b32 s19, s19, 3
	s_add_u32 s16, s6, s19
	s_addc_u32 s17, s7, 0
	s_cmp_lt_u32 s8, s9
	s_waitcnt vmcnt(2)
	s_barrier
	s_cbranch_scc1 .Lat_loop_0
	s_branch .Lat_epilogue
